# v22 = v21 + attention loop: loop-invariant K/V source select hoisted (32-bit offsets, SGPR-base loads), S-m via v_pk_add_f32
# baseline (speedup 1.0000x reference)
.LBB0_703:
	s_or_b64 exec, exec, s[0:1]
	s_add_u32 s0, s8, 0x144d7900
	s_addc_u32 s1, s9, 0
	v_ashrrev_i32_e32 v9, 3, v4
	v_lshl_add_u32 v1, s50, 8, v1
	v_lshlrev_b32_e32 v122, 3, v5
	v_add_u32_e32 v5, v1, v9
	v_mov_b64_e32 v[28:29], s[0:1]
	v_lshlrev_b32_e32 v4, 4, v4
	v_ashrrev_i32_e32 v15, 3, v16
	global_load_dwordx4 v[232:235], v[26:27], off
	v_mad_i64_i32 v[26:27], s[24:25], v5, s71, 0
	v_mad_i64_i32 v[30:31], s[0:1], v5, s71, v[28:29]
	v_and_b32_e32 v4, 0x70, v4
	v_mov_b32_e32 v5, v117
	v_add_u32_e32 v1, v1, v15
	v_lshl_add_u64 v[30:31], v[30:31], 0, v[4:5]
	v_mad_i64_i32 v[28:29], s[0:1], v1, s71, v[28:29]
	v_lshl_add_u64 v[28:29], v[28:29], 0, v[4:5]
	global_load_dwordx4 v[236:239], v[30:31], off
	global_load_dwordx4 v[240:243], v[28:29], off
	v_and_b32_e32 v5, 64, v161
	v_mad_i64_i32 v[16:17], s[0:1], v1, s71, 0
	v_xor_b32_e32 v1, 32, v161
	v_add_u32_e32 v5, 64, v5
	v_cmp_lt_i32_e64 s[0:1], v1, v5
	s_mul_i32 s16, s50, 0x24000
	v_lshlrev_b32_e32 v25, 4, v8
	v_cndmask_b32_e64 v1, v161, v1, s[0:1]
	s_add_i32 s0, s51, 1
	v_or_b32_e32 v8, 32, v116
	s_mul_hi_i32 s1, s50, 0x24000
	s_add_u32 s24, s16, 0x14298900
	v_lshlrev_b32_e32 v123, 2, v1
	v_mul_u32_u24_e32 v163, 0x90, v116
	v_mul_u32_u24_e32 v1, 0xd0, v116
	v_mul_lo_u32 v35, v9, s72
	v_mul_u32_u24_e32 v116, 0x90, v8
	s_addc_u32 s25, s1, 0
	v_lshlrev_b64 v[8:9], 6, v[18:19]
	s_mul_i32 s16, s50, 0x120000
	v_lshl_add_u64 v[8:9], s[24:25], 0, v[8:9]
	s_mul_hi_i32 s1, s50, 0x120000
	s_add_u32 s26, s16, 0x1309f900
	v_lshl_add_u64 v[128:129], v[22:23], 1, v[8:9]
	s_addc_u32 s27, s1, 0
	v_lshlrev_b64 v[8:9], 9, v[18:19]
	v_lshlrev_b32_e32 v33, 4, v14
	v_mul_lo_u32 v36, v15, s72
	v_lshl_add_u64 v[8:9], s[26:27], 0, v[8:9]
	v_lshl_add_u64 v[14:15], v[20:21], 0, v[120:121]
	v_lshl_add_u64 v[130:131], v[14:15], 1, v[8:9]
	v_lshlrev_b64 v[8:9], 6, v[10:11]
	v_subrev_u32_e32 v30, 64, v12
	v_mov_b32_e32 v31, v117
	v_lshl_add_u64 v[8:9], s[24:25], 0, v[8:9]
	v_lshl_add_u64 v[132:133], v[30:31], 1, v[8:9]
	v_lshlrev_b64 v[8:9], 9, v[10:11]
	v_mul_lo_u32 v32, v10, s73
	v_lshl_add_u64 v[8:9], s[26:27], 0, v[8:9]
	v_lshl_add_u64 v[10:11], v[120:121], 0, v[12:13]
	v_mul_lo_u32 v5, v2, s73
	v_lshl_add_u64 v[134:135], v[10:11], 1, v[8:9]
	v_lshlrev_b64 v[8:9], 6, v[2:3]
	v_lshlrev_b64 v[2:3], 9, v[2:3]
	v_subrev_u32_e32 v28, 64, v6
	v_mov_b32_e32 v29, v117
	v_mul_lo_u32 v34, v18, s73
	v_lshlrev_b32_e32 v24, 4, v24
	v_or_b32_e32 v16, v16, v4
	v_or_b32_e32 v26, v26, v4
	v_lshl_add_u64 v[8:9], s[24:25], 0, v[8:9]
	v_lshl_add_u64 v[2:3], s[26:27], 0, v[2:3]
	v_lshl_add_u64 v[6:7], v[120:121], 0, v[6:7]
	v_mov_b32_e32 v104, 0
	v_sub_u32_e32 v162, v0, v122
	v_lshl_add_u64 v[124:125], v[16:17], 0, s[40:41]
	v_lshl_add_u64 v[126:127], v[26:27], 0, s[40:41]
	v_lshl_add_u64 v[136:137], v[28:29], 1, v[8:9]
	v_lshl_add_u64 v[138:139], v[6:7], 1, v[2:3]
	v_mov_b32_e32 v105, 0xf149f2ca
	v_add_u32_e32 v165, v5, v25
	v_add_u32_e32 v166, v32, v33
	v_add_u32_e32 v167, v34, v24
	v_add_u32_e32 v168, v4, v35
	v_add_u32_e32 v169, v4, v36
	v_add_u32_e32 v164, v0, v1
	v_mov_b32_e32 v0, 0
	v_mov_b32_e32 v1, v104
	v_mov_b32_e32 v2, v104
	v_mov_b32_e32 v3, v104
	v_mov_b32_e32 v4, v104
	v_mov_b32_e32 v5, v104
	v_mov_b32_e32 v6, v104
	v_mov_b32_e32 v7, v104
	v_mov_b32_e32 v8, v104
	v_mov_b32_e32 v9, v104
	v_mov_b32_e32 v10, v104
	v_mov_b32_e32 v11, v104
	v_mov_b32_e32 v12, v104
	v_mov_b32_e32 v13, v104
	v_mov_b32_e32 v14, v104
	v_mov_b32_e32 v15, v104
	v_mov_b32_e32 v16, 0
	v_mov_b32_e32 v17, v104
	v_mov_b32_e32 v18, v104
	v_mov_b32_e32 v19, v104
	v_mov_b32_e32 v20, v104
	v_mov_b32_e32 v21, v104
	v_mov_b32_e32 v22, v104
	v_mov_b32_e32 v23, v104
	v_mov_b32_e32 v24, v104
	v_mov_b32_e32 v25, v104
	v_mov_b32_e32 v26, v104
	v_mov_b32_e32 v27, v104
	v_mov_b32_e32 v28, v104
	v_mov_b32_e32 v29, v104
	v_mov_b32_e32 v30, v104
	v_mov_b32_e32 v31, v104
	v_cndmask_b32_e32 v138, v136, v138, vcc
	v_mov_b32_e32 v245, s44
	v_mov_b32_e32 v248, s46
	v_cndmask_b32_e32 v245, v245, v248, vcc
	v_cndmask_b32_e64 v134, v132, v134, s[4:5]
	v_mov_b32_e32 v246, s44
	v_mov_b32_e32 v248, s46
	v_cndmask_b32_e64 v246, v246, v248, s[4:5]
	v_cndmask_b32_e64 v130, v128, v130, s[6:7]
	v_mov_b32_e32 v247, s44
	v_mov_b32_e32 v248, s46
	v_cndmask_b32_e64 v247, v247, v248, s[6:7]
.LBB0_704:
	s_waitcnt lgkmcnt(0)
	s_barrier
	s_waitcnt vmcnt(0)
	ds_write_b128 v165, v[224:227]
	ds_write_b128 v166, v[228:231]
	ds_write_b128 v167, v[232:235]
	ds_write_b128 v168, v[236:239] offset:13312
	ds_write_b128 v169, v[240:243] offset:13312
	s_waitcnt lgkmcnt(0)
	s_barrier
	ds_read_b128 v[32:35], v164
	ds_read_b128 v[88:91], v164 offset:32
	global_load_dwordx4 v[236:239], v126, s[8:9]
	global_load_dwordx4 v[240:243], v124, s[8:9]
	global_load_dwordx4 v[224:227], v138, s[8:9]
	global_load_dwordx4 v[228:231], v134, s[8:9]
	global_load_dwordx4 v[232:235], v130, s[8:9]
	s_waitcnt lgkmcnt(1)
	v_mfma_f32_32x32x16_bf16 v[32:47], v[32:35], v[84:87], 0
	ds_read_b128 v[48:51], v164 offset:6656
	ds_read_b128 v[92:95], v164 offset:6688
	v_mov_b32_e32 v171, v105
	v_mov_b32_e32 v170, v104
	s_waitcnt lgkmcnt(1)
	v_mfma_f32_32x32x16_bf16 v[48:63], v[48:51], v[84:87], 0
	v_mfma_f32_32x32x16_bf16 v[32:47], v[88:91], v[80:83], v[32:47]
	ds_read_b128 v[88:91], v164 offset:64
	v_add_u32_e32 v172, v122, v163
	v_add_u32_e32 v143, 0x3000, v172
	v_add_u32_e32 v173, v122, v116
	s_waitcnt lgkmcnt(1)
	v_mfma_f32_32x32x16_bf16 v[48:63], v[92:95], v[80:83], v[48:63]
	ds_read_b128 v[100:103], v164 offset:96
	ds_read_b128 v[92:95], v164 offset:6720
	ds_read_b128 v[96:99], v164 offset:6752
	v_add_u32_e32 v174, v162, v163
	v_add_u32_e32 v175, v162, v116
	v_add_u32_e32 v142, 0x3000, v173
	v_add_u32_e32 v141, 0x3000, v174
	v_add_u32_e32 v140, 0x3000, v175
	s_waitcnt lgkmcnt(3)
	v_mfma_f32_32x32x16_bf16 v[32:47], v[88:91], v[76:79], v[32:47]
	s_add_i32 s0, s0, -1
	v_add_u32_e32 v126, s42, v126
	v_add_u32_e32 v124, s42, v124
	v_add_u32_e32 v138, v245, v138
	v_add_u32_e32 v134, v246, v134
	v_add_u32_e32 v130, v247, v130
	s_waitcnt lgkmcnt(1)
	v_mfma_f32_32x32x16_bf16 v[48:63], v[92:95], v[76:79], v[48:63]
	ds_read_b128 v[88:91], v164 offset:128
	ds_read_b128 v[104:107], v164 offset:160
	ds_read_b128 v[92:95], v164 offset:6784
	ds_read_b128 v[108:111], v164 offset:6816
	s_cmp_lg_u32 s0, 0
	v_mfma_f32_32x32x16_bf16 v[32:47], v[100:103], v[72:75], v[32:47]
	s_waitcnt lgkmcnt(4)
	v_mfma_f32_32x32x16_bf16 v[48:63], v[96:99], v[72:75], v[48:63]
	s_waitcnt lgkmcnt(0)
	v_mfma_f32_32x32x16_bf16 v[32:47], v[88:91], v[68:71], v[32:47]
	v_mfma_f32_32x32x16_bf16 v[48:63], v[92:95], v[68:71], v[48:63]
	s_nop 0
	ds_read2_b64 v[144:147], v143 offset0:128 offset1:130
	ds_read2_b64 v[148:151], v143 offset0:132 offset1:134
	ds_read2_b64 v[172:175], v142 offset0:128 offset1:130
	ds_read2_b64 v[176:179], v142 offset0:132 offset1:134
	ds_read2_b64 v[180:183], v143 offset0:136 offset1:138
	ds_read2_b64 v[184:187], v142 offset0:136 offset1:138
	ds_read2_b64 v[188:191], v141 offset0:140 offset1:142
	ds_read2_b64 v[192:195], v140 offset0:140 offset1:142
	v_mfma_f32_32x32x16_bf16 v[32:47], v[104:107], v[64:67], v[32:47]
	v_mfma_f32_32x32x16_bf16 v[48:63], v[108:111], v[64:67], v[48:63]
	s_nop 10
	v_max_f32_e32 v104, v33, v33
	v_max_f32_e32 v105, v32, v32
	v_max_f32_e32 v104, v105, v104
	v_max3_f32 v104, v104, v34, v35
	v_max3_f32 v104, v104, v36, v37
	v_max3_f32 v104, v104, v38, v39
	v_max3_f32 v104, v104, v40, v41
	v_max3_f32 v104, v104, v42, v43
	v_max3_f32 v104, v104, v44, v45
	v_max3_f32 v104, v104, v46, v47
	v_max3_f32 v104, v104, v48, v49
	v_max3_f32 v104, v104, v50, v51
	v_max3_f32 v104, v104, v52, v53
	v_max3_f32 v104, v104, v54, v55
	v_max3_f32 v104, v104, v56, v57
	v_max3_f32 v104, v104, v58, v59
	v_max3_f32 v104, v104, v60, v61
	v_max3_f32 v104, v104, v62, v63
	ds_bpermute_b32 v105, v123, v104
	s_waitcnt lgkmcnt(0)
	v_max3_f32 v105, v171, v104, v105
	v_sub_f32_e32 v104, v171, v105
	v_pk_add_f32 v[32:33], v[32:33], v[104:105] op_sel:[0,1] op_sel_hi:[1,1] neg_lo:[0,1] neg_hi:[0,1]
	v_pk_add_f32 v[34:35], v[34:35], v[104:105] op_sel:[0,1] op_sel_hi:[1,1] neg_lo:[0,1] neg_hi:[0,1]
	v_pk_add_f32 v[36:37], v[36:37], v[104:105] op_sel:[0,1] op_sel_hi:[1,1] neg_lo:[0,1] neg_hi:[0,1]
	v_pk_add_f32 v[38:39], v[38:39], v[104:105] op_sel:[0,1] op_sel_hi:[1,1] neg_lo:[0,1] neg_hi:[0,1]
	v_sub_f32_e32 v106, v42, v105
	v_exp_f32_e32 v42, v104
	v_exp_f32_e32 v32, v32
	v_exp_f32_e32 v33, v33
	s_nop 0
	v_cvt_pk_bf16_f32 v244, v32, v33
	v_exp_f32_e32 v104, v34
	v_exp_f32_e32 v107, v35
	v_exp_f32_e32 v108, v36
	v_exp_f32_e32 v109, v37
	v_exp_f32_e32 v110, v38
	v_exp_f32_e32 v111, v39
	v_sub_f32_e32 v43, v43, v105
	v_pk_add_f32 v[40:41], v[40:41], v[104:105] op_sel:[0,1] op_sel_hi:[1,1] neg_lo:[0,1] neg_hi:[0,1]
	v_exp_f32_e32 v43, v43
	v_exp_f32_e32 v171, v40
	v_exp_f32_e32 v196, v41
	v_add_f32_e32 v34, 0, v32
	v_add_f32_e32 v222, v33, v34
	v_pk_add_f32 v[44:45], v[44:45], v[104:105] op_sel:[0,1] op_sel_hi:[1,1] neg_lo:[0,1] neg_hi:[0,1]
	v_pk_add_f32 v[46:47], v[46:47], v[104:105] op_sel:[0,1] op_sel_hi:[1,1] neg_lo:[0,1] neg_hi:[0,1]
	v_pk_mul_f32 v[30:31], v[30:31], v[42:43] op_sel_hi:[1,0]
	v_pk_mul_f32 v[28:29], v[28:29], v[42:43] op_sel_hi:[1,0]
	v_pk_mul_f32 v[26:27], v[26:27], v[42:43] op_sel_hi:[1,0]
	v_pk_mul_f32 v[24:25], v[24:25], v[42:43] op_sel_hi:[1,0]
	v_pk_mul_f32 v[22:23], v[22:23], v[42:43] op_sel_hi:[1,0]
	v_pk_mul_f32 v[20:21], v[20:21], v[42:43] op_sel_hi:[1,0]
	v_pk_mul_f32 v[18:19], v[18:19], v[42:43] op_sel_hi:[1,0]
	v_pk_mul_f32 v[16:17], v[16:17], v[42:43] op_sel_hi:[1,0]
	v_pk_mul_f32 v[14:15], v[14:15], v[42:43] op_sel_hi:[1,0]
	v_pk_mul_f32 v[12:13], v[12:13], v[42:43] op_sel_hi:[1,0]
	v_pk_mul_f32 v[10:11], v[10:11], v[42:43] op_sel_hi:[1,0]
	v_pk_mul_f32 v[8:9], v[8:9], v[42:43] op_sel_hi:[1,0]
	v_pk_mul_f32 v[6:7], v[6:7], v[42:43] op_sel_hi:[1,0]
	v_pk_mul_f32 v[4:5], v[4:5], v[42:43] op_sel_hi:[1,0]
	v_pk_mul_f32 v[2:3], v[2:3], v[42:43] op_sel_hi:[1,0]
	v_pk_mul_f32 v[0:1], v[0:1], v[42:43] op_sel_hi:[1,0]
	v_cvt_pk_bf16_f32 v35, v110, v111
	v_cvt_pk_bf16_f32 v34, v108, v109
	v_cvt_pk_bf16_f32 v33, v104, v107
	v_mov_b32_e32 v32, v244
	v_exp_f32_e32 v106, v106
	v_exp_f32_e32 v44, v44
	v_exp_f32_e32 v45, v45
	v_exp_f32_e32 v46, v46
	v_mfma_f32_32x32x16_bf16 v[16:31], v[144:147], v[32:35], v[16:31]
	v_exp_f32_e32 v47, v47
	v_mfma_f32_32x32x16_bf16 v[0:15], v[172:175], v[32:35], v[0:15]
	v_add_f32_e32 v37, v104, v222
	v_cvt_pk_bf16_f32 v35, v46, v47
	v_cvt_pk_bf16_f32 v34, v44, v45
	v_cvt_pk_bf16_f32 v33, v106, v43
	v_cvt_pk_bf16_f32 v32, v171, v196
	v_add_f32_e32 v104, v107, v37
	v_pk_add_f32 v[48:49], v[48:49], v[104:105] op_sel:[0,1] op_sel_hi:[1,1] neg_lo:[0,1] neg_hi:[0,1]
	v_mfma_f32_32x32x16_bf16 v[16:31], v[148:151], v[32:35], v[16:31]
	v_pk_add_f32 v[50:51], v[50:51], v[104:105] op_sel:[0,1] op_sel_hi:[1,1] neg_lo:[0,1] neg_hi:[0,1]
	v_pk_add_f32 v[52:53], v[52:53], v[104:105] op_sel:[0,1] op_sel_hi:[1,1] neg_lo:[0,1] neg_hi:[0,1]
	v_pk_add_f32 v[54:55], v[54:55], v[104:105] op_sel:[0,1] op_sel_hi:[1,1] neg_lo:[0,1] neg_hi:[0,1]
	v_mfma_f32_32x32x16_bf16 v[0:15], v[176:179], v[32:35], v[0:15]
	v_add_f32_e32 v32, v108, v104
	v_add_f32_e32 v32, v109, v32
	v_add_f32_e32 v32, v110, v32
	v_add_f32_e32 v32, v111, v32
	v_add_f32_e32 v32, v171, v32
	v_pk_add_f32 v[56:57], v[56:57], v[104:105] op_sel:[0,1] op_sel_hi:[1,1] neg_lo:[0,1] neg_hi:[0,1]
	v_exp_f32_e32 v48, v48
	v_exp_f32_e32 v49, v49
	v_exp_f32_e32 v50, v50
	v_exp_f32_e32 v51, v51
	v_exp_f32_e32 v52, v52
	v_exp_f32_e32 v53, v53
	v_exp_f32_e32 v54, v54
	v_add_f32_e32 v32, v196, v32
	v_exp_f32_e32 v55, v55
	v_exp_f32_e32 v56, v56
	v_add_f32_e32 v32, v106, v32
	v_add_f32_e32 v32, v43, v32
	v_add_f32_e32 v32, v44, v32
	v_add_f32_e32 v32, v45, v32
	v_add_f32_e32 v32, v46, v32
	v_add_f32_e32 v32, v47, v32
	v_pk_add_f32 v[58:59], v[58:59], v[104:105] op_sel:[0,1] op_sel_hi:[1,1] neg_lo:[0,1] neg_hi:[0,1]
	v_pk_add_f32 v[60:61], v[60:61], v[104:105] op_sel:[0,1] op_sel_hi:[1,1] neg_lo:[0,1] neg_hi:[0,1]
	v_pk_add_f32 v[62:63], v[62:63], v[104:105] op_sel:[0,1] op_sel_hi:[1,1] neg_lo:[0,1] neg_hi:[0,1]
	v_cvt_pk_bf16_f32 v37, v54, v55
	v_cvt_pk_bf16_f32 v36, v52, v53
	v_cvt_pk_bf16_f32 v35, v50, v51
	v_cvt_pk_bf16_f32 v34, v48, v49
	v_add_f32_e32 v32, v48, v32
	v_exp_f32_e32 v57, v57
	v_exp_f32_e32 v58, v58
	v_exp_f32_e32 v59, v59
	v_exp_f32_e32 v60, v60
	v_exp_f32_e32 v61, v61
	v_exp_f32_e32 v62, v62
	v_mfma_f32_32x32x16_bf16 v[16:31], v[180:183], v[34:37], v[16:31]
	v_add_f32_e32 v32, v49, v32
	v_exp_f32_e32 v63, v63
	v_add_f32_e32 v32, v50, v32
	v_add_f32_e32 v32, v51, v32
	v_add_f32_e32 v32, v52, v32
	v_mfma_f32_32x32x16_bf16 v[0:15], v[184:187], v[34:37], v[0:15]
	v_add_f32_e32 v32, v53, v32
	v_add_f32_e32 v32, v54, v32
	v_add_f32_e32 v32, v55, v32
	v_cvt_pk_bf16_f32 v41, v62, v63
	v_cvt_pk_bf16_f32 v40, v60, v61
	v_cvt_pk_bf16_f32 v39, v58, v59
	v_cvt_pk_bf16_f32 v38, v56, v57
	v_add_f32_e32 v32, v56, v32
	v_add_f32_e32 v32, v57, v32
	v_mfma_f32_32x32x16_bf16 v[16:31], v[188:191], v[38:41], v[16:31]
	v_add_f32_e32 v32, v58, v32
	v_add_f32_e32 v32, v59, v32
	v_add_f32_e32 v32, v60, v32
	v_add_f32_e32 v32, v61, v32
	v_add_f32_e32 v32, v62, v32
	v_add_f32_e32 v104, v63, v32
	v_fmac_f32_e32 v104, v170, v42
	v_mfma_f32_32x32x16_bf16 v[0:15], v[192:195], v[38:41], v[0:15]
	s_cbranch_scc1 .LBB0_704
	s_barrier
	s_waitcnt vmcnt(0)
	ds_write_b128 v165, v[224:227]
	ds_write_b128 v166, v[228:231]
	ds_write_b128 v167, v[232:235]
	ds_write_b128 v168, v[236:239] offset:13312
	ds_write_b128 v169, v[240:243] offset:13312
	s_waitcnt lgkmcnt(0)
	s_barrier
	ds_read_b128 v[32:35], v164
	ds_read_b128 v[36:39], v164 offset:32
	s_waitcnt lgkmcnt(1)
	v_mfma_f32_32x32x16_bf16 v[48:63], v[32:35], v[84:87], 0
	s_waitcnt lgkmcnt(0)
	v_mfma_f32_32x32x16_bf16 v[48:63], v[36:39], v[80:83], v[48:63]
	ds_read_b128 v[32:35], v164 offset:64
	ds_read_b128 v[36:39], v164 offset:96
	s_waitcnt lgkmcnt(1)
	v_mfma_f32_32x32x16_bf16 v[48:63], v[32:35], v[76:79], v[48:63]
	s_waitcnt lgkmcnt(0)
	v_mfma_f32_32x32x16_bf16 v[48:63], v[36:39], v[72:75], v[48:63]
	ds_read_b128 v[32:35], v164 offset:128
	ds_read_b128 v[36:39], v164 offset:160
	s_waitcnt lgkmcnt(1)
	v_mfma_f32_32x32x16_bf16 v[48:63], v[32:35], v[68:71], v[48:63]
	ds_read_b128 v[32:35], v164 offset:6656
	ds_read_b128 v[88:91], v164 offset:6688
	s_waitcnt lgkmcnt(2)
	v_mfma_f32_32x32x16_bf16 v[48:63], v[36:39], v[64:67], v[48:63]
	s_waitcnt lgkmcnt(1)
	v_mfma_f32_32x32x16_bf16 v[32:47], v[32:35], v[84:87], 0
	s_waitcnt lgkmcnt(0)
	v_mfma_f32_32x32x16_bf16 v[32:47], v[88:91], v[80:83], v[32:47]
	ds_read_b128 v[80:83], v164 offset:6720
	ds_read_b128 v[84:87], v164 offset:6752
	s_waitcnt lgkmcnt(1)
	v_mfma_f32_32x32x16_bf16 v[32:47], v[80:83], v[76:79], v[32:47]
	s_nop 3
	v_max_f32_e32 v80, v49, v49
	v_max_f32_e32 v81, v48, v48
	v_max_f32_e32 v80, v81, v80
	s_waitcnt lgkmcnt(0)
	v_mfma_f32_32x32x16_bf16 v[32:47], v[84:87], v[72:75], v[32:47]
	ds_read_b128 v[72:75], v164 offset:6784
	ds_read_b128 v[76:79], v164 offset:6816
	s_waitcnt lgkmcnt(1)
	v_mfma_f32_32x32x16_bf16 v[32:47], v[72:75], v[68:71], v[32:47]
	v_max3_f32 v68, v80, v50, v51
	v_max3_f32 v68, v68, v52, v53
	v_max3_f32 v68, v68, v54, v55
	v_max3_f32 v68, v68, v56, v57
	v_max3_f32 v68, v68, v58, v59
	v_max3_f32 v68, v68, v60, v61
	v_max3_f32 v68, v68, v62, v63
	s_waitcnt lgkmcnt(0)
	v_mfma_f32_32x32x16_bf16 v[32:47], v[76:79], v[64:67], v[32:47]
	s_nop 11
	v_max3_f32 v64, v68, v32, v33
	v_max3_f32 v64, v64, v34, v35
	v_max3_f32 v64, v64, v36, v37
	v_max3_f32 v64, v64, v38, v39
	v_max3_f32 v64, v64, v40, v41
	v_max3_f32 v64, v64, v42, v43
	v_max3_f32 v64, v64, v44, v45
	v_max3_f32 v64, v64, v46, v47
	ds_bpermute_b32 v65, v123, v64
	s_waitcnt lgkmcnt(0)
	v_max3_f32 v65, v105, v64, v65
	v_sub_f32_e32 v32, v32, v65
	v_exp_f32_e32 v66, v32
	v_sub_f32_e32 v32, v33, v65
	v_exp_f32_e32 v67, v32
	v_sub_f32_e32 v32, v34, v65
	v_exp_f32_e32 v68, v32
	v_sub_f32_e32 v32, v35, v65
	v_exp_f32_e32 v69, v32
	v_sub_f32_e32 v32, v36, v65
	v_exp_f32_e32 v70, v32
	v_sub_f32_e32 v32, v37, v65
	v_exp_f32_e32 v71, v32
	v_sub_f32_e32 v32, v38, v65
	v_exp_f32_e32 v72, v32
	v_sub_f32_e32 v32, v39, v65
	v_exp_f32_e32 v73, v32
	v_sub_f32_e32 v32, v40, v65
	v_exp_f32_e32 v74, v32
	v_sub_f32_e32 v32, v41, v65
	v_exp_f32_e32 v75, v32
	v_sub_f32_e32 v32, v42, v65
	v_sub_f32_e32 v48, v48, v65
	v_exp_f32_e32 v76, v32
	v_sub_f32_e32 v32, v43, v65
	v_exp_f32_e32 v48, v48
	v_sub_f32_e32 v49, v49, v65
	v_exp_f32_e32 v77, v32
	v_sub_f32_e32 v32, v44, v65
	v_exp_f32_e32 v49, v49
	v_sub_f32_e32 v50, v50, v65
	v_sub_f32_e32 v55, v55, v65
	v_exp_f32_e32 v78, v32
	v_sub_f32_e32 v32, v45, v65
	v_exp_f32_e32 v50, v50
	v_sub_f32_e32 v51, v51, v65
	v_sub_f32_e32 v53, v53, v65
	v_exp_f32_e32 v55, v55
	v_exp_f32_e32 v79, v32
	v_sub_f32_e32 v32, v46, v65
	v_exp_f32_e32 v51, v51
	v_sub_f32_e32 v52, v52, v65
	v_exp_f32_e32 v53, v53
	v_sub_f32_e32 v54, v54, v65
	v_exp_f32_e32 v80, v32
	v_sub_f32_e32 v32, v47, v65
	v_sub_f32_e32 v64, v105, v65
	v_exp_f32_e32 v52, v52
	v_exp_f32_e32 v54, v54
	v_sub_f32_e32 v56, v56, v65
	v_sub_f32_e32 v57, v57, v65
	v_sub_f32_e32 v58, v58, v65
	v_sub_f32_e32 v59, v59, v65
	v_sub_f32_e32 v60, v60, v65
	v_sub_f32_e32 v61, v61, v65
	v_sub_f32_e32 v62, v62, v65
	v_sub_f32_e32 v63, v63, v65
	v_exp_f32_e32 v65, v32
	v_add_f32_e32 v32, 0, v48
	v_add_f32_e32 v32, v49, v32
	v_add_f32_e32 v44, v50, v32
	ds_read2_b64 v[32:35], v143 offset0:128 offset1:130
	v_exp_f32_e32 v64, v64
	v_cvt_pk_bf16_f32 v39, v54, v55
	v_cvt_pk_bf16_f32 v38, v52, v53
	v_cvt_pk_bf16_f32 v37, v50, v51
	v_cvt_pk_bf16_f32 v36, v48, v49
	ds_read2_b64 v[40:43], v142 offset0:128 offset1:130
	v_pk_mul_f32 v[30:31], v[30:31], v[64:65] op_sel_hi:[1,0]
	v_pk_mul_f32 v[28:29], v[28:29], v[64:65] op_sel_hi:[1,0]
	v_pk_mul_f32 v[26:27], v[26:27], v[64:65] op_sel_hi:[1,0]
	v_pk_mul_f32 v[24:25], v[24:25], v[64:65] op_sel_hi:[1,0]
	v_pk_mul_f32 v[22:23], v[22:23], v[64:65] op_sel_hi:[1,0]
	v_pk_mul_f32 v[20:21], v[20:21], v[64:65] op_sel_hi:[1,0]
	v_pk_mul_f32 v[18:19], v[18:19], v[64:65] op_sel_hi:[1,0]
	v_pk_mul_f32 v[16:17], v[16:17], v[64:65] op_sel_hi:[1,0]
	v_exp_f32_e32 v57, v57
	v_exp_f32_e32 v59, v59
	s_waitcnt lgkmcnt(1)
	v_mfma_f32_32x32x16_bf16 v[16:31], v[32:35], v[36:39], v[16:31]
	v_add_f32_e32 v32, v51, v44
	v_exp_f32_e32 v56, v56
	v_exp_f32_e32 v58, v58
	v_exp_f32_e32 v60, v60
	v_exp_f32_e32 v62, v62
	v_add_f32_e32 v32, v52, v32
	v_exp_f32_e32 v61, v61
	v_exp_f32_e32 v63, v63
	v_add_f32_e32 v32, v53, v32
	v_pk_mul_f32 v[14:15], v[14:15], v[64:65] op_sel_hi:[1,0]
	v_pk_mul_f32 v[12:13], v[12:13], v[64:65] op_sel_hi:[1,0]
	v_pk_mul_f32 v[10:11], v[10:11], v[64:65] op_sel_hi:[1,0]
	v_pk_mul_f32 v[8:9], v[8:9], v[64:65] op_sel_hi:[1,0]
	v_pk_mul_f32 v[6:7], v[6:7], v[64:65] op_sel_hi:[1,0]
	v_pk_mul_f32 v[4:5], v[4:5], v[64:65] op_sel_hi:[1,0]
	v_pk_mul_f32 v[2:3], v[2:3], v[64:65] op_sel_hi:[1,0]
	v_pk_mul_f32 v[0:1], v[0:1], v[64:65] op_sel_hi:[1,0]
	v_add_f32_e32 v32, v54, v32
	v_add_f32_e32 v48, v55, v32
	s_waitcnt lgkmcnt(0)
	v_mfma_f32_32x32x16_bf16 v[0:15], v[40:43], v[36:39], v[0:15]
	ds_read2_b64 v[32:35], v143 offset0:132 offset1:134
	ds_read2_b64 v[44:47], v142 offset0:132 offset1:134
	v_add_f32_e32 v40, v56, v48
	v_cvt_pk_bf16_f32 v39, v62, v63
	v_cvt_pk_bf16_f32 v38, v60, v61
	v_cvt_pk_bf16_f32 v37, v58, v59
	v_cvt_pk_bf16_f32 v36, v56, v57
	s_waitcnt lgkmcnt(1)
	s_nop 0
	v_mfma_f32_32x32x16_bf16 v[16:31], v[32:35], v[36:39], v[16:31]
	v_add_f32_e32 v32, v57, v40
	v_add_f32_e32 v32, v58, v32
	v_add_f32_e32 v32, v59, v32
	v_add_f32_e32 v32, v60, v32
	v_add_f32_e32 v32, v61, v32
	v_add_f32_e32 v32, v62, v32
	v_add_f32_e32 v32, v63, v32
	s_waitcnt lgkmcnt(0)
	v_mfma_f32_32x32x16_bf16 v[0:15], v[44:47], v[36:39], v[0:15]
	v_add_f32_e32 v44, v66, v32
	ds_read2_b64 v[32:35], v143 offset0:136 offset1:138
	v_cvt_pk_bf16_f32 v39, v72, v73
	v_cvt_pk_bf16_f32 v38, v70, v71
	v_cvt_pk_bf16_f32 v37, v68, v69
	v_cvt_pk_bf16_f32 v36, v66, v67
	ds_read2_b64 v[40:43], v142 offset0:136 offset1:138
	s_waitcnt lgkmcnt(1)
	v_mfma_f32_32x32x16_bf16 v[16:31], v[32:35], v[36:39], v[16:31]
	v_add_f32_e32 v32, v67, v44
	v_add_f32_e32 v32, v68, v32
	v_add_f32_e32 v32, v69, v32
	v_add_f32_e32 v32, v70, v32
	v_add_f32_e32 v32, v71, v32
	v_add_f32_e32 v32, v72, v32
	v_add_f32_e32 v32, v73, v32
	v_add_f32_e32 v32, v74, v32
	v_add_f32_e32 v32, v75, v32
	v_add_f32_e32 v32, v76, v32
	v_add_f32_e32 v32, v77, v32
	v_add_f32_e32 v32, v78, v32
	v_add_f32_e32 v32, v79, v32
	v_add_f32_e32 v32, v80, v32
	s_waitcnt lgkmcnt(0)
	v_mfma_f32_32x32x16_bf16 v[0:15], v[40:43], v[36:39], v[0:15]
	v_add_f32_e32 v40, v65, v32
	ds_read2_b64 v[32:35], v141 offset0:140 offset1:142
	v_fmac_f32_e32 v40, v104, v64
	v_cvt_pk_bf16_f32 v39, v80, v65
	ds_bpermute_b32 v41, v123, v40
	v_cvt_pk_bf16_f32 v38, v78, v79
	v_cvt_pk_bf16_f32 v37, v76, v77
	v_cvt_pk_bf16_f32 v36, v74, v75
	v_mov_b32_e32 v123, v117
	s_waitcnt lgkmcnt(0)
	v_add_f32_e32 v40, v40, v41
	v_mfma_f32_32x32x16_bf16 v[16:31], v[32:35], v[36:39], v[16:31]
	ds_read2_b64 v[32:35], v140 offset0:140 offset1:142
	v_div_scale_f32 v41, s[0:1], v40, v40, 1.0
	v_rcp_f32_e32 v42, v41
	s_waitcnt lgkmcnt(0)
	v_mfma_f32_32x32x16_bf16 v[0:15], v[32:35], v[36:39], v[0:15]
	v_fma_f32 v32, -v41, v42, 1.0
	v_fmac_f32_e32 v42, v32, v42
	v_div_scale_f32 v32, vcc, 1.0, v40, 1.0
	v_mul_f32_e32 v33, v32, v42
	v_fma_f32 v34, -v41, v33, v32
	v_fmac_f32_e32 v33, v34, v42
	v_fma_f32 v32, -v41, v33, v32
	v_div_fmas_f32 v32, v32, v42, v33
	v_div_fixup_f32 v32, v32, v40, 1.0
	v_mov_b32_e32 v38, v16
	v_mov_b32_e32 v39, v18
	v_mov_b32_e32 v18, v17
	v_lshlrev_b64 v[34:35], 11, v[118:119]
	v_pk_mul_f32 v[38:39], v[38:39], v[32:33] op_sel_hi:[1,0]
	v_pk_mul_f32 v[16:17], v[18:19], v[32:33] op_sel_hi:[1,0]
	v_lshl_add_u64 v[34:35], s[8:9], 0, v[34:35]
	v_and_b32_sdwa v19, v38, v159 dst_sel:DWORD dst_unused:UNUSED_PAD src0_sel:WORD_1 src1_sel:DWORD
	v_and_b32_sdwa v33, v17, v159 dst_sel:DWORD dst_unused:UNUSED_PAD src0_sel:WORD_1 src1_sel:DWORD
	v_lshl_add_u64 v[34:35], v[120:121], 1, v[34:35]
	v_and_b32_sdwa v18, v39, v159 dst_sel:DWORD dst_unused:UNUSED_PAD src0_sel:WORD_1 src1_sel:DWORD
	v_add3_u32 v19, v38, v19, s59
	v_and_b32_sdwa v38, v16, v159 dst_sel:DWORD dst_unused:UNUSED_PAD src0_sel:WORD_1 src1_sel:DWORD
	v_add3_u32 v17, v17, v33, s59
	v_lshl_add_u64 v[34:35], v[34:35], 0, v[122:123]
	v_add3_u32 v18, v39, v18, s59
	v_add3_u32 v16, v16, v38, s59
	v_and_b32_e32 v17, 0xffff0000, v17
	v_and_b32_e32 v16, 0xffff0000, v16
	v_or_b32_sdwa v17, v17, v18 dst_sel:DWORD dst_unused:UNUSED_PAD src0_sel:DWORD src1_sel:WORD_1
	v_add_co_u32_e32 v18, vcc, s61, v34
	v_or_b32_sdwa v16, v16, v19 dst_sel:DWORD dst_unused:UNUSED_PAD src0_sel:DWORD src1_sel:WORD_1
	s_nop 0
	v_addc_co_u32_e32 v19, vcc, 0, v35, vcc
	global_store_dwordx2 v[18:19], v[16:17], off offset:3840
	v_mov_b32_e32 v16, v20
	v_mov_b32_e32 v17, v22
	v_pk_mul_f32 v[16:17], v[16:17], v[32:33] op_sel_hi:[1,0]
	v_mov_b32_e32 v22, v21
	v_pk_mul_f32 v[18:19], v[22:23], v[32:33] op_sel_hi:[1,0]
	v_and_b32_sdwa v20, v17, v159 dst_sel:DWORD dst_unused:UNUSED_PAD src0_sel:WORD_1 src1_sel:DWORD
	v_and_b32_sdwa v21, v16, v159 dst_sel:DWORD dst_unused:UNUSED_PAD src0_sel:WORD_1 src1_sel:DWORD
	v_add3_u32 v16, v16, v21, s59
	v_add3_u32 v17, v17, v20, s59
	v_and_b32_sdwa v20, v19, v159 dst_sel:DWORD dst_unused:UNUSED_PAD src0_sel:WORD_1 src1_sel:DWORD
	v_and_b32_sdwa v21, v18, v159 dst_sel:DWORD dst_unused:UNUSED_PAD src0_sel:WORD_1 src1_sel:DWORD
	v_add3_u32 v19, v19, v20, s59
	v_add3_u32 v18, v18, v21, s59
	v_and_b32_e32 v19, 0xffff0000, v19
	v_and_b32_e32 v18, 0xffff0000, v18
	v_lshl_add_u64 v[36:37], v[34:35], 0, s[48:49]
	v_or_b32_sdwa v17, v19, v17 dst_sel:DWORD dst_unused:UNUSED_PAD src0_sel:DWORD src1_sel:WORD_1
	v_or_b32_sdwa v16, v18, v16 dst_sel:DWORD dst_unused:UNUSED_PAD src0_sel:DWORD src1_sel:WORD_1
	global_store_dwordx2 v[36:37], v[16:17], off offset:16
	v_mov_b32_e32 v16, v24
	v_mov_b32_e32 v17, v26
	v_pk_mul_f32 v[16:17], v[16:17], v[32:33] op_sel_hi:[1,0]
	v_mov_b32_e32 v26, v25
	v_pk_mul_f32 v[18:19], v[26:27], v[32:33] op_sel_hi:[1,0]
	v_and_b32_sdwa v20, v17, v159 dst_sel:DWORD dst_unused:UNUSED_PAD src0_sel:WORD_1 src1_sel:DWORD
	v_and_b32_sdwa v21, v16, v159 dst_sel:DWORD dst_unused:UNUSED_PAD src0_sel:WORD_1 src1_sel:DWORD
	v_add3_u32 v16, v16, v21, s59
	v_add3_u32 v17, v17, v20, s59
	v_and_b32_sdwa v20, v19, v159 dst_sel:DWORD dst_unused:UNUSED_PAD src0_sel:WORD_1 src1_sel:DWORD
	v_and_b32_sdwa v21, v18, v159 dst_sel:DWORD dst_unused:UNUSED_PAD src0_sel:WORD_1 src1_sel:DWORD
	v_add3_u32 v19, v19, v20, s59
	v_add3_u32 v18, v18, v21, s59
	v_and_b32_e32 v19, 0xffff0000, v19
	v_and_b32_e32 v18, 0xffff0000, v18
	v_or_b32_sdwa v17, v19, v17 dst_sel:DWORD dst_unused:UNUSED_PAD src0_sel:DWORD src1_sel:WORD_1
	v_or_b32_sdwa v16, v18, v16 dst_sel:DWORD dst_unused:UNUSED_PAD src0_sel:DWORD src1_sel:WORD_1
	global_store_dwordx2 v[36:37], v[16:17], off offset:32
	v_mov_b32_e32 v16, v28
	v_mov_b32_e32 v17, v30
	v_pk_mul_f32 v[16:17], v[16:17], v[32:33] op_sel_hi:[1,0]
	v_mov_b32_e32 v30, v29
	v_pk_mul_f32 v[18:19], v[30:31], v[32:33] op_sel_hi:[1,0]
	v_and_b32_sdwa v20, v17, v159 dst_sel:DWORD dst_unused:UNUSED_PAD src0_sel:WORD_1 src1_sel:DWORD
	v_and_b32_sdwa v21, v16, v159 dst_sel:DWORD dst_unused:UNUSED_PAD src0_sel:WORD_1 src1_sel:DWORD
	v_add3_u32 v16, v16, v21, s59
	v_add3_u32 v17, v17, v20, s59
	v_and_b32_sdwa v20, v19, v159 dst_sel:DWORD dst_unused:UNUSED_PAD src0_sel:WORD_1 src1_sel:DWORD
	v_and_b32_sdwa v21, v18, v159 dst_sel:DWORD dst_unused:UNUSED_PAD src0_sel:WORD_1 src1_sel:DWORD
	v_add3_u32 v19, v19, v20, s59
	v_add3_u32 v18, v18, v21, s59
	v_and_b32_e32 v19, 0xffff0000, v19
	v_and_b32_e32 v18, 0xffff0000, v18
	v_or_b32_sdwa v17, v19, v17 dst_sel:DWORD dst_unused:UNUSED_PAD src0_sel:DWORD src1_sel:WORD_1
	v_or_b32_sdwa v16, v18, v16 dst_sel:DWORD dst_unused:UNUSED_PAD src0_sel:DWORD src1_sel:WORD_1
	global_store_dwordx2 v[36:37], v[16:17], off offset:48
	v_mov_b32_e32 v16, v0
	v_mov_b32_e32 v17, v2
	v_pk_mul_f32 v[16:17], v[16:17], v[32:33] op_sel_hi:[1,0]
	v_mov_b32_e32 v2, v1
	v_pk_mul_f32 v[0:1], v[2:3], v[32:33] op_sel_hi:[1,0]
	v_and_b32_sdwa v2, v17, v159 dst_sel:DWORD dst_unused:UNUSED_PAD src0_sel:WORD_1 src1_sel:DWORD
	v_and_b32_sdwa v3, v16, v159 dst_sel:DWORD dst_unused:UNUSED_PAD src0_sel:WORD_1 src1_sel:DWORD
	v_add3_u32 v3, v16, v3, s59
	v_add3_u32 v2, v17, v2, s59
	v_and_b32_sdwa v16, v1, v159 dst_sel:DWORD dst_unused:UNUSED_PAD src0_sel:WORD_1 src1_sel:DWORD
	v_and_b32_sdwa v17, v0, v159 dst_sel:DWORD dst_unused:UNUSED_PAD src0_sel:WORD_1 src1_sel:DWORD
	v_add3_u32 v1, v1, v16, s59
	v_add3_u32 v0, v0, v17, s59
	v_and_b32_e32 v1, 0xffff0000, v1
	v_and_b32_e32 v0, 0xffff0000, v0
	v_or_b32_sdwa v1, v1, v2 dst_sel:DWORD dst_unused:UNUSED_PAD src0_sel:DWORD src1_sel:WORD_1
	v_or_b32_sdwa v0, v0, v3 dst_sel:DWORD dst_unused:UNUSED_PAD src0_sel:DWORD src1_sel:WORD_1
	global_store_dwordx2 v[36:37], v[0:1], off offset:64
	v_mov_b32_e32 v0, v4
	v_mov_b32_e32 v1, v6
	v_pk_mul_f32 v[0:1], v[0:1], v[32:33] op_sel_hi:[1,0]
	v_mov_b32_e32 v6, v5
	v_pk_mul_f32 v[2:3], v[6:7], v[32:33] op_sel_hi:[1,0]
	v_and_b32_sdwa v4, v1, v159 dst_sel:DWORD dst_unused:UNUSED_PAD src0_sel:WORD_1 src1_sel:DWORD
	v_and_b32_sdwa v5, v0, v159 dst_sel:DWORD dst_unused:UNUSED_PAD src0_sel:WORD_1 src1_sel:DWORD
	v_add3_u32 v0, v0, v5, s59
	v_add3_u32 v1, v1, v4, s59
	v_and_b32_sdwa v4, v3, v159 dst_sel:DWORD dst_unused:UNUSED_PAD src0_sel:WORD_1 src1_sel:DWORD
	v_and_b32_sdwa v5, v2, v159 dst_sel:DWORD dst_unused:UNUSED_PAD src0_sel:WORD_1 src1_sel:DWORD
	v_add3_u32 v3, v3, v4, s59
	v_add3_u32 v2, v2, v5, s59
	v_and_b32_e32 v3, 0xffff0000, v3
	v_and_b32_e32 v2, 0xffff0000, v2
	v_or_b32_sdwa v1, v3, v1 dst_sel:DWORD dst_unused:UNUSED_PAD src0_sel:DWORD src1_sel:WORD_1
	v_or_b32_sdwa v0, v2, v0 dst_sel:DWORD dst_unused:UNUSED_PAD src0_sel:DWORD src1_sel:WORD_1
	global_store_dwordx2 v[36:37], v[0:1], off offset:80
	v_mov_b32_e32 v0, v8
	v_mov_b32_e32 v1, v10
	v_pk_mul_f32 v[0:1], v[0:1], v[32:33] op_sel_hi:[1,0]
	v_mov_b32_e32 v10, v9
	v_pk_mul_f32 v[2:3], v[10:11], v[32:33] op_sel_hi:[1,0]
	v_and_b32_sdwa v4, v1, v159 dst_sel:DWORD dst_unused:UNUSED_PAD src0_sel:WORD_1 src1_sel:DWORD
	v_and_b32_sdwa v5, v0, v159 dst_sel:DWORD dst_unused:UNUSED_PAD src0_sel:WORD_1 src1_sel:DWORD
	v_add3_u32 v0, v0, v5, s59
	v_add3_u32 v1, v1, v4, s59
	v_and_b32_sdwa v4, v3, v159 dst_sel:DWORD dst_unused:UNUSED_PAD src0_sel:WORD_1 src1_sel:DWORD
	v_and_b32_sdwa v5, v2, v159 dst_sel:DWORD dst_unused:UNUSED_PAD src0_sel:WORD_1 src1_sel:DWORD
	v_add3_u32 v3, v3, v4, s59
	v_add3_u32 v2, v2, v5, s59
	v_and_b32_e32 v3, 0xffff0000, v3
	v_and_b32_e32 v2, 0xffff0000, v2
	v_or_b32_sdwa v1, v3, v1 dst_sel:DWORD dst_unused:UNUSED_PAD src0_sel:DWORD src1_sel:WORD_1
	v_or_b32_sdwa v0, v2, v0 dst_sel:DWORD dst_unused:UNUSED_PAD src0_sel:DWORD src1_sel:WORD_1
	global_store_dwordx2 v[36:37], v[0:1], off offset:96
	v_mov_b32_e32 v0, v12
	v_mov_b32_e32 v1, v14
	v_pk_mul_f32 v[0:1], v[0:1], v[32:33] op_sel_hi:[1,0]
	v_mov_b32_e32 v14, v13
	v_pk_mul_f32 v[2:3], v[14:15], v[32:33] op_sel_hi:[1,0]
	v_and_b32_sdwa v4, v1, v159 dst_sel:DWORD dst_unused:UNUSED_PAD src0_sel:WORD_1 src1_sel:DWORD
	v_and_b32_sdwa v5, v0, v159 dst_sel:DWORD dst_unused:UNUSED_PAD src0_sel:WORD_1 src1_sel:DWORD
	v_add3_u32 v0, v0, v5, s59
	v_add3_u32 v1, v1, v4, s59
	v_and_b32_sdwa v4, v3, v159 dst_sel:DWORD dst_unused:UNUSED_PAD src0_sel:WORD_1 src1_sel:DWORD
	v_and_b32_sdwa v5, v2, v159 dst_sel:DWORD dst_unused:UNUSED_PAD src0_sel:WORD_1 src1_sel:DWORD
	v_add3_u32 v3, v3, v4, s59
	v_add3_u32 v2, v2, v5, s59
	v_and_b32_e32 v3, 0xffff0000, v3
	v_and_b32_e32 v2, 0xffff0000, v2
	v_or_b32_sdwa v1, v3, v1 dst_sel:DWORD dst_unused:UNUSED_PAD src0_sel:DWORD src1_sel:WORD_1
	v_or_b32_sdwa v0, v2, v0 dst_sel:DWORD dst_unused:UNUSED_PAD src0_sel:DWORD src1_sel:WORD_1
	global_store_dwordx2 v[36:37], v[0:1], off offset:112
	s_branch .LBB0_579

.LBB0_1683:
	s_or_b64 exec, exec, s[0:1]
	s_add_u32 s0, s8, 0x144d7900
	s_addc_u32 s1, s9, 0
	v_ashrrev_i32_e32 v13, 3, v2
	v_lshl_add_u32 v7, s52, 8, v7
	v_lshlrev_b32_e32 v2, 4, v2
	v_lshlrev_b32_e32 v122, 3, v15
	v_add_u32_e32 v15, v7, v13
	v_mov_b64_e32 v[26:27], s[0:1]
	v_and_b32_e32 v30, 0x70, v2
	v_ashrrev_i32_e32 v2, 3, v14
	v_mad_i64_i32 v[28:29], s[0:1], v15, s73, v[26:27]
	v_mov_b32_e32 v31, v117
	v_add_u32_e32 v7, v7, v2
	v_lshl_add_u64 v[28:29], v[28:29], 0, v[30:31]
	v_mad_i64_i32 v[26:27], s[0:1], v7, s73, v[26:27]
	global_load_dwordx4 v[232:235], v[24:25], off
	v_lshl_add_u64 v[26:27], v[26:27], 0, v[30:31]
	global_load_dwordx4 v[236:239], v[28:29], off
	global_load_dwordx4 v[240:243], v[26:27], off
	v_and_b32_e32 v23, 64, v157
	v_mad_i64_i32 v[24:25], s[24:25], v15, s73, 0
	v_mad_i64_i32 v[14:15], s[0:1], v7, s73, 0
	v_xor_b32_e32 v7, 32, v157
	v_add_u32_e32 v23, 64, v23
	v_cmp_lt_i32_e64 s[0:1], v7, v23
	v_mul_lo_u32 v35, v2, s75
	v_or_b32_e32 v2, 32, v3
	v_cndmask_b32_e64 v7, v157, v7, s[0:1]
	s_mul_i32 s0, s52, 0x24000
	s_mul_hi_i32 s1, s52, 0x24000
	s_add_u32 s0, s0, 0x14298900
	v_mul_u32_u24_e32 v159, 0x90, v3
	v_mul_u32_u24_e32 v23, 0xd0, v3
	v_mul_u32_u24_e32 v160, 0x90, v2
	s_addc_u32 s1, s1, 0
	v_lshlrev_b64 v[2:3], 6, v[16:17]
	s_mul_hi_i32 s16, s52, 0x120000
	s_mul_i32 s52, s52, 0x120000
	v_lshl_add_u64 v[2:3], s[0:1], 0, v[2:3]
	s_add_u32 s24, s52, 0x1309f900
	v_lshl_add_u64 v[128:129], v[20:21], 1, v[2:3]
	s_addc_u32 s25, s16, 0
	v_lshlrev_b64 v[2:3], 9, v[16:17]
	v_lshlrev_b32_e32 v123, 2, v7
	v_lshlrev_b32_e32 v32, 4, v6
	v_lshl_add_u64 v[2:3], s[24:25], 0, v[2:3]
	v_lshl_add_u64 v[6:7], v[18:19], 0, v[120:121]
	v_lshl_add_u64 v[130:131], v[6:7], 1, v[2:3]
	v_lshlrev_b64 v[2:3], 6, v[8:9]
	v_subrev_u32_e32 v28, 64, v10
	v_mov_b32_e32 v29, v117
	v_lshl_add_u64 v[2:3], s[0:1], 0, v[2:3]
	v_lshl_add_u64 v[132:133], v[28:29], 1, v[2:3]
	v_lshlrev_b64 v[2:3], 9, v[8:9]
	v_lshl_add_u64 v[2:3], s[24:25], 0, v[2:3]
	v_lshl_add_u64 v[6:7], v[120:121], 0, v[10:11]
	v_lshl_add_u64 v[134:135], v[6:7], 1, v[2:3]
	v_lshlrev_b64 v[2:3], 6, v[0:1]
	v_subrev_u32_e32 v26, 64, v4
	v_mov_b32_e32 v27, v117
	v_mul_lo_u32 v31, v0, s76
	v_lshl_add_u64 v[2:3], s[0:1], 0, v[2:3]
	v_lshlrev_b64 v[0:1], 9, v[0:1]
	v_mul_lo_u32 v33, v8, s76
	v_lshlrev_b32_e32 v12, 4, v12
	v_mul_lo_u32 v34, v16, s76
	v_lshlrev_b32_e32 v22, 4, v22
	v_mul_lo_u32 v13, v13, s75
	v_or_b32_e32 v14, v14, v30
	v_or_b32_e32 v24, v24, v30
	v_lshl_add_u64 v[136:137], v[26:27], 1, v[2:3]
	v_lshl_add_u64 v[0:1], s[24:25], 0, v[0:1]
	v_lshl_add_u64 v[2:3], v[120:121], 0, v[4:5]
	v_mov_b32_e32 v108, 0
	v_sub_u32_e32 v158, v116, v122
	v_lshl_add_u64 v[124:125], v[14:15], 0, s[42:43]
	v_lshl_add_u64 v[126:127], v[24:25], 0, s[42:43]
	v_lshl_add_u64 v[138:139], v[2:3], 1, v[0:1]
	v_mov_b32_e32 v109, 0xf149f2ca
	s_mov_b32 s0, 35
	v_add_u32_e32 v161, v31, v32
	v_add_u32_e32 v162, v33, v12
	v_add_u32_e32 v163, v34, v22
	v_add_u32_e32 v164, v30, v13
	v_add_u32_e32 v165, v30, v35
	v_add_u32_e32 v116, v116, v23
	v_mov_b32_e32 v0, 0
	v_mov_b32_e32 v1, v108
	v_mov_b32_e32 v2, v108
	v_mov_b32_e32 v3, v108
	v_mov_b32_e32 v4, v108
	v_mov_b32_e32 v5, v108
	v_mov_b32_e32 v6, v108
	v_mov_b32_e32 v7, v108
	v_mov_b32_e32 v8, v108
	v_mov_b32_e32 v9, v108
	v_mov_b32_e32 v10, v108
	v_mov_b32_e32 v11, v108
	v_mov_b32_e32 v12, v108
	v_mov_b32_e32 v13, v108
	v_mov_b32_e32 v14, v108
	v_mov_b32_e32 v15, v108
	v_mov_b32_e32 v16, 0
	v_mov_b32_e32 v17, v108
	v_mov_b32_e32 v18, v108
	v_mov_b32_e32 v19, v108
	v_mov_b32_e32 v20, v108
	v_mov_b32_e32 v21, v108
	v_mov_b32_e32 v22, v108
	v_mov_b32_e32 v23, v108
	v_mov_b32_e32 v24, v108
	v_mov_b32_e32 v25, v108
	v_mov_b32_e32 v26, v108
	v_mov_b32_e32 v27, v108
	v_mov_b32_e32 v28, v108
	v_mov_b32_e32 v29, v108
	v_mov_b32_e32 v30, v108
	v_mov_b32_e32 v31, v108
	v_cndmask_b32_e32 v138, v136, v138, vcc
	v_mov_b32_e32 v245, s46
	v_mov_b32_e32 v248, s48
	v_cndmask_b32_e32 v245, v245, v248, vcc
	v_cndmask_b32_e64 v134, v132, v134, s[4:5]
	v_mov_b32_e32 v246, s46
	v_mov_b32_e32 v248, s48
	v_cndmask_b32_e64 v246, v246, v248, s[4:5]
	v_cndmask_b32_e64 v130, v128, v130, s[6:7]
	v_mov_b32_e32 v247, s46
	v_mov_b32_e32 v248, s48
	v_cndmask_b32_e64 v247, v247, v248, s[6:7]
.LBB0_1684:
	s_waitcnt lgkmcnt(0)
	s_barrier
	s_waitcnt vmcnt(0)
	ds_write_b128 v161, v[224:227]
	ds_write_b128 v162, v[228:231]
	ds_write_b128 v163, v[232:235]
	ds_write_b128 v164, v[236:239] offset:13312
	ds_write_b128 v165, v[240:243] offset:13312
	s_waitcnt lgkmcnt(0)
	s_barrier
	ds_read_b128 v[32:35], v116
	ds_read_b128 v[88:91], v116 offset:32
	global_load_dwordx4 v[236:239], v126, s[8:9]
	global_load_dwordx4 v[240:243], v124, s[8:9]
	global_load_dwordx4 v[224:227], v138, s[8:9]
	global_load_dwordx4 v[228:231], v134, s[8:9]
	global_load_dwordx4 v[232:235], v130, s[8:9]
	s_waitcnt lgkmcnt(1)
	v_mfma_f32_32x32x16_bf16 v[32:47], v[32:35], v[84:87], 0
	ds_read_b128 v[48:51], v116 offset:6656
	ds_read_b128 v[92:95], v116 offset:6688
	v_mov_b32_e32 v167, v109
	v_mov_b32_e32 v166, v108
	s_waitcnt lgkmcnt(1)
	v_mfma_f32_32x32x16_bf16 v[48:63], v[48:51], v[84:87], 0
	v_add_u32_e32 v172, v122, v159
	v_add_u32_e32 v173, v122, v160
	s_add_i32 s0, s0, -1
	v_mfma_f32_32x32x16_bf16 v[32:47], v[88:91], v[80:83], v[32:47]
	ds_read_b128 v[88:91], v116 offset:64
	v_add_u32_e32 v126, s44, v126
	v_add_u32_e32 v124, s44, v124
	v_add_u32_e32 v138, v245, v138
	v_add_u32_e32 v134, v246, v134
	v_add_u32_e32 v130, v247, v130
	s_waitcnt lgkmcnt(1)
	v_mfma_f32_32x32x16_bf16 v[48:63], v[92:95], v[80:83], v[48:63]
	ds_read_b128 v[168:171], v116 offset:96
	ds_read_b128 v[92:95], v116 offset:6720
	ds_read_b128 v[96:99], v116 offset:6752
	s_cmp_lg_u32 s0, 0
	s_waitcnt lgkmcnt(3)
	v_mfma_f32_32x32x16_bf16 v[32:47], v[88:91], v[76:79], v[32:47]
	s_waitcnt lgkmcnt(1)
	v_mfma_f32_32x32x16_bf16 v[48:63], v[92:95], v[76:79], v[48:63]
	ds_read_b128 v[92:95], v116 offset:128
	ds_read_b128 v[112:115], v116 offset:160
	ds_read_b128 v[88:91], v116 offset:6784
	ds_read_b128 v[108:111], v116 offset:6816
	v_mfma_f32_32x32x16_bf16 v[32:47], v[168:171], v[72:75], v[32:47]
	v_add_u32_e32 v168, v158, v159
	v_add_u32_e32 v169, v158, v160
	s_waitcnt lgkmcnt(4)
	v_mfma_f32_32x32x16_bf16 v[48:63], v[96:99], v[72:75], v[48:63]
	s_waitcnt lgkmcnt(0)
	v_mfma_f32_32x32x16_bf16 v[32:47], v[92:95], v[68:71], v[32:47]
	v_add_u32_e32 v143, 0x3000, v172
	v_add_u32_e32 v142, 0x3000, v173
	v_add_u32_e32 v141, 0x3000, v168
	v_add_u32_e32 v140, 0x3000, v169
	v_mfma_f32_32x32x16_bf16 v[48:63], v[88:91], v[68:71], v[48:63]
	s_nop 0
	ds_read2_b64 v[144:147], v143 offset0:128 offset1:130
	v_mfma_f32_32x32x16_bf16 v[32:47], v[112:115], v[64:67], v[32:47]
	ds_read2_b64 v[112:115], v143 offset0:132 offset1:134
	ds_read2_b64 v[168:171], v142 offset0:128 offset1:130
	ds_read2_b64 v[172:175], v142 offset0:132 offset1:134
	ds_read2_b64 v[176:179], v143 offset0:136 offset1:138
	ds_read2_b64 v[180:183], v142 offset0:136 offset1:138
	ds_read2_b64 v[184:187], v141 offset0:140 offset1:142
	ds_read2_b64 v[188:191], v140 offset0:140 offset1:142
	v_mfma_f32_32x32x16_bf16 v[48:63], v[108:111], v[64:67], v[48:63]
	s_nop 3
	v_max_f32_e32 v108, v33, v33
	v_max_f32_e32 v109, v32, v32
	v_max_f32_e32 v108, v109, v108
	v_max3_f32 v108, v108, v34, v35
	v_max3_f32 v108, v108, v36, v37
	v_max3_f32 v108, v108, v38, v39
	v_max3_f32 v108, v108, v40, v41
	v_max3_f32 v108, v108, v42, v43
	v_max3_f32 v108, v108, v44, v45
	v_max3_f32 v108, v108, v46, v47
	v_max3_f32 v108, v108, v48, v49
	v_max3_f32 v108, v108, v50, v51
	v_max3_f32 v108, v108, v52, v53
	v_max3_f32 v108, v108, v54, v55
	v_max3_f32 v108, v108, v56, v57
	v_max3_f32 v108, v108, v58, v59
	v_max3_f32 v108, v108, v60, v61
	v_max3_f32 v108, v108, v62, v63
	ds_bpermute_b32 v109, v123, v108
	s_waitcnt lgkmcnt(0)
	v_max3_f32 v109, v167, v108, v109
	v_sub_f32_e32 v108, v167, v109
	v_pk_add_f32 v[32:33], v[32:33], v[108:109] op_sel:[0,1] op_sel_hi:[1,1] neg_lo:[0,1] neg_hi:[0,1]
	v_pk_add_f32 v[34:35], v[34:35], v[108:109] op_sel:[0,1] op_sel_hi:[1,1] neg_lo:[0,1] neg_hi:[0,1]
	v_pk_add_f32 v[36:37], v[36:37], v[108:109] op_sel:[0,1] op_sel_hi:[1,1] neg_lo:[0,1] neg_hi:[0,1]
	v_pk_add_f32 v[38:39], v[38:39], v[108:109] op_sel:[0,1] op_sel_hi:[1,1] neg_lo:[0,1] neg_hi:[0,1]
	v_sub_f32_e32 v110, v42, v109
	v_exp_f32_e32 v42, v108
	v_exp_f32_e32 v32, v32
	v_exp_f32_e32 v33, v33
	s_nop 0
	v_cvt_pk_bf16_f32 v244, v32, v33
	v_exp_f32_e32 v108, v34
	v_exp_f32_e32 v111, v35
	v_exp_f32_e32 v167, v36
	v_exp_f32_e32 v192, v37
	v_exp_f32_e32 v193, v38
	v_exp_f32_e32 v194, v39
	v_sub_f32_e32 v43, v43, v109
	v_pk_add_f32 v[40:41], v[40:41], v[108:109] op_sel:[0,1] op_sel_hi:[1,1] neg_lo:[0,1] neg_hi:[0,1]
	v_exp_f32_e32 v43, v43
	v_exp_f32_e32 v195, v40
	v_exp_f32_e32 v196, v41
	v_add_f32_e32 v34, 0, v32
	v_add_f32_e32 v222, v33, v34
	v_pk_add_f32 v[44:45], v[44:45], v[108:109] op_sel:[0,1] op_sel_hi:[1,1] neg_lo:[0,1] neg_hi:[0,1]
	v_pk_add_f32 v[46:47], v[46:47], v[108:109] op_sel:[0,1] op_sel_hi:[1,1] neg_lo:[0,1] neg_hi:[0,1]
	v_pk_mul_f32 v[30:31], v[30:31], v[42:43] op_sel_hi:[1,0]
	v_pk_mul_f32 v[28:29], v[28:29], v[42:43] op_sel_hi:[1,0]
	v_pk_mul_f32 v[26:27], v[26:27], v[42:43] op_sel_hi:[1,0]
	v_pk_mul_f32 v[24:25], v[24:25], v[42:43] op_sel_hi:[1,0]
	v_pk_mul_f32 v[22:23], v[22:23], v[42:43] op_sel_hi:[1,0]
	v_pk_mul_f32 v[20:21], v[20:21], v[42:43] op_sel_hi:[1,0]
	v_pk_mul_f32 v[18:19], v[18:19], v[42:43] op_sel_hi:[1,0]
	v_pk_mul_f32 v[16:17], v[16:17], v[42:43] op_sel_hi:[1,0]
	v_pk_mul_f32 v[14:15], v[14:15], v[42:43] op_sel_hi:[1,0]
	v_pk_mul_f32 v[12:13], v[12:13], v[42:43] op_sel_hi:[1,0]
	v_pk_mul_f32 v[10:11], v[10:11], v[42:43] op_sel_hi:[1,0]
	v_pk_mul_f32 v[8:9], v[8:9], v[42:43] op_sel_hi:[1,0]
	v_pk_mul_f32 v[6:7], v[6:7], v[42:43] op_sel_hi:[1,0]
	v_pk_mul_f32 v[4:5], v[4:5], v[42:43] op_sel_hi:[1,0]
	v_pk_mul_f32 v[2:3], v[2:3], v[42:43] op_sel_hi:[1,0]
	v_pk_mul_f32 v[0:1], v[0:1], v[42:43] op_sel_hi:[1,0]
	v_cvt_pk_bf16_f32 v35, v193, v194
	v_cvt_pk_bf16_f32 v34, v167, v192
	v_cvt_pk_bf16_f32 v33, v108, v111
	v_mov_b32_e32 v32, v244
	v_exp_f32_e32 v110, v110
	v_exp_f32_e32 v44, v44
	v_exp_f32_e32 v45, v45
	v_exp_f32_e32 v46, v46
	v_mfma_f32_32x32x16_bf16 v[16:31], v[144:147], v[32:35], v[16:31]
	v_exp_f32_e32 v47, v47
	v_mfma_f32_32x32x16_bf16 v[0:15], v[168:171], v[32:35], v[0:15]
	v_add_f32_e32 v37, v108, v222
	v_cvt_pk_bf16_f32 v35, v46, v47
	v_cvt_pk_bf16_f32 v34, v44, v45
	v_cvt_pk_bf16_f32 v33, v110, v43
	v_cvt_pk_bf16_f32 v32, v195, v196
	v_add_f32_e32 v108, v111, v37
	v_pk_add_f32 v[48:49], v[48:49], v[108:109] op_sel:[0,1] op_sel_hi:[1,1] neg_lo:[0,1] neg_hi:[0,1]
	v_mfma_f32_32x32x16_bf16 v[16:31], v[112:115], v[32:35], v[16:31]
	v_pk_add_f32 v[50:51], v[50:51], v[108:109] op_sel:[0,1] op_sel_hi:[1,1] neg_lo:[0,1] neg_hi:[0,1]
	v_pk_add_f32 v[52:53], v[52:53], v[108:109] op_sel:[0,1] op_sel_hi:[1,1] neg_lo:[0,1] neg_hi:[0,1]
	v_pk_add_f32 v[54:55], v[54:55], v[108:109] op_sel:[0,1] op_sel_hi:[1,1] neg_lo:[0,1] neg_hi:[0,1]
	v_mfma_f32_32x32x16_bf16 v[0:15], v[172:175], v[32:35], v[0:15]
	v_add_f32_e32 v32, v167, v108
	v_add_f32_e32 v32, v192, v32
	v_add_f32_e32 v32, v193, v32
	v_add_f32_e32 v32, v194, v32
	v_add_f32_e32 v32, v195, v32
	v_pk_add_f32 v[56:57], v[56:57], v[108:109] op_sel:[0,1] op_sel_hi:[1,1] neg_lo:[0,1] neg_hi:[0,1]
	v_exp_f32_e32 v48, v48
	v_exp_f32_e32 v49, v49
	v_exp_f32_e32 v50, v50
	v_exp_f32_e32 v51, v51
	v_exp_f32_e32 v52, v52
	v_exp_f32_e32 v53, v53
	v_exp_f32_e32 v54, v54
	v_add_f32_e32 v32, v196, v32
	v_exp_f32_e32 v55, v55
	v_exp_f32_e32 v56, v56
	v_add_f32_e32 v32, v110, v32
	v_add_f32_e32 v32, v43, v32
	v_add_f32_e32 v32, v44, v32
	v_add_f32_e32 v32, v45, v32
	v_add_f32_e32 v32, v46, v32
	v_add_f32_e32 v32, v47, v32
	v_pk_add_f32 v[58:59], v[58:59], v[108:109] op_sel:[0,1] op_sel_hi:[1,1] neg_lo:[0,1] neg_hi:[0,1]
	v_pk_add_f32 v[60:61], v[60:61], v[108:109] op_sel:[0,1] op_sel_hi:[1,1] neg_lo:[0,1] neg_hi:[0,1]
	v_pk_add_f32 v[62:63], v[62:63], v[108:109] op_sel:[0,1] op_sel_hi:[1,1] neg_lo:[0,1] neg_hi:[0,1]
	v_cvt_pk_bf16_f32 v37, v54, v55
	v_cvt_pk_bf16_f32 v36, v52, v53
	v_cvt_pk_bf16_f32 v35, v50, v51
	v_cvt_pk_bf16_f32 v34, v48, v49
	v_add_f32_e32 v32, v48, v32
	v_exp_f32_e32 v57, v57
	v_exp_f32_e32 v58, v58
	v_exp_f32_e32 v59, v59
	v_exp_f32_e32 v60, v60
	v_exp_f32_e32 v61, v61
	v_exp_f32_e32 v62, v62
	v_mfma_f32_32x32x16_bf16 v[16:31], v[176:179], v[34:37], v[16:31]
	v_add_f32_e32 v32, v49, v32
	v_exp_f32_e32 v63, v63
	v_add_f32_e32 v32, v50, v32
	v_add_f32_e32 v32, v51, v32
	v_add_f32_e32 v32, v52, v32
	v_mfma_f32_32x32x16_bf16 v[0:15], v[180:183], v[34:37], v[0:15]
	v_add_f32_e32 v32, v53, v32
	v_add_f32_e32 v32, v54, v32
	v_add_f32_e32 v32, v55, v32
	v_cvt_pk_bf16_f32 v41, v62, v63
	v_cvt_pk_bf16_f32 v40, v60, v61
	v_cvt_pk_bf16_f32 v39, v58, v59
	v_cvt_pk_bf16_f32 v38, v56, v57
	v_add_f32_e32 v32, v56, v32
	v_add_f32_e32 v32, v57, v32
	v_mfma_f32_32x32x16_bf16 v[16:31], v[184:187], v[38:41], v[16:31]
	v_add_f32_e32 v32, v58, v32
	v_add_f32_e32 v32, v59, v32
	v_add_f32_e32 v32, v60, v32
	v_add_f32_e32 v32, v61, v32
	v_add_f32_e32 v32, v62, v32
	v_add_f32_e32 v108, v63, v32
	v_fmac_f32_e32 v108, v166, v42
	v_mfma_f32_32x32x16_bf16 v[0:15], v[188:191], v[38:41], v[0:15]
	s_cbranch_scc1 .LBB0_1684
	s_barrier
	s_waitcnt vmcnt(0)
	ds_write_b128 v161, v[224:227]
	ds_write_b128 v162, v[228:231]
	ds_write_b128 v163, v[232:235]
	ds_write_b128 v164, v[236:239] offset:13312
	ds_write_b128 v165, v[240:243] offset:13312
	s_waitcnt lgkmcnt(0)
	s_barrier
	ds_read_b128 v[32:35], v116
	ds_read_b128 v[36:39], v116 offset:32
	s_waitcnt lgkmcnt(1)
	v_mfma_f32_32x32x16_bf16 v[48:63], v[32:35], v[84:87], 0
	s_waitcnt lgkmcnt(0)
	v_mfma_f32_32x32x16_bf16 v[48:63], v[36:39], v[80:83], v[48:63]
	ds_read_b128 v[32:35], v116 offset:64
	ds_read_b128 v[36:39], v116 offset:96
	s_waitcnt lgkmcnt(1)
	v_mfma_f32_32x32x16_bf16 v[48:63], v[32:35], v[76:79], v[48:63]
	s_waitcnt lgkmcnt(0)
	v_mfma_f32_32x32x16_bf16 v[48:63], v[36:39], v[72:75], v[48:63]
	ds_read_b128 v[32:35], v116 offset:128
	ds_read_b128 v[36:39], v116 offset:160
	s_waitcnt lgkmcnt(1)
	v_mfma_f32_32x32x16_bf16 v[48:63], v[32:35], v[68:71], v[48:63]
	ds_read_b128 v[32:35], v116 offset:6656
	ds_read_b128 v[88:91], v116 offset:6688
	s_waitcnt lgkmcnt(2)
	v_mfma_f32_32x32x16_bf16 v[48:63], v[36:39], v[64:67], v[48:63]
	s_waitcnt lgkmcnt(1)
	v_mfma_f32_32x32x16_bf16 v[32:47], v[32:35], v[84:87], 0
	s_waitcnt lgkmcnt(0)
	v_mfma_f32_32x32x16_bf16 v[32:47], v[88:91], v[80:83], v[32:47]
	ds_read_b128 v[80:83], v116 offset:6720
	ds_read_b128 v[84:87], v116 offset:6752
	s_waitcnt lgkmcnt(1)
	v_mfma_f32_32x32x16_bf16 v[32:47], v[80:83], v[76:79], v[32:47]
	s_nop 3
	v_max_f32_e32 v80, v49, v49
	v_max_f32_e32 v81, v48, v48
	v_max_f32_e32 v80, v81, v80
	s_waitcnt lgkmcnt(0)
	v_mfma_f32_32x32x16_bf16 v[32:47], v[84:87], v[72:75], v[32:47]
	ds_read_b128 v[72:75], v116 offset:6784
	ds_read_b128 v[76:79], v116 offset:6816
	s_waitcnt lgkmcnt(1)
	v_mfma_f32_32x32x16_bf16 v[32:47], v[72:75], v[68:71], v[32:47]
	v_max3_f32 v68, v80, v50, v51
	v_max3_f32 v68, v68, v52, v53
	v_max3_f32 v68, v68, v54, v55
	v_max3_f32 v68, v68, v56, v57
	v_max3_f32 v68, v68, v58, v59
	v_max3_f32 v68, v68, v60, v61
	v_max3_f32 v68, v68, v62, v63
	s_waitcnt lgkmcnt(0)
	v_mfma_f32_32x32x16_bf16 v[32:47], v[76:79], v[64:67], v[32:47]
	s_nop 11
	v_max3_f32 v64, v68, v32, v33
	v_max3_f32 v64, v64, v34, v35
	v_max3_f32 v64, v64, v36, v37
	v_max3_f32 v64, v64, v38, v39
	v_max3_f32 v64, v64, v40, v41
	v_max3_f32 v64, v64, v42, v43
	v_max3_f32 v64, v64, v44, v45
	v_max3_f32 v64, v64, v46, v47
	ds_bpermute_b32 v65, v123, v64
	s_waitcnt lgkmcnt(0)
	v_max3_f32 v65, v109, v64, v65
	v_sub_f32_e32 v32, v32, v65
	v_exp_f32_e32 v66, v32
	v_sub_f32_e32 v32, v33, v65
	v_exp_f32_e32 v67, v32
	v_sub_f32_e32 v32, v34, v65
	v_exp_f32_e32 v68, v32
	v_sub_f32_e32 v32, v35, v65
	v_exp_f32_e32 v69, v32
	v_sub_f32_e32 v32, v36, v65
	v_exp_f32_e32 v70, v32
	v_sub_f32_e32 v32, v37, v65
	v_exp_f32_e32 v71, v32
	v_sub_f32_e32 v32, v38, v65
	v_exp_f32_e32 v72, v32
	v_sub_f32_e32 v32, v39, v65
	v_exp_f32_e32 v73, v32
	v_sub_f32_e32 v32, v40, v65
	v_exp_f32_e32 v74, v32
	v_sub_f32_e32 v32, v41, v65
	v_exp_f32_e32 v75, v32
	v_sub_f32_e32 v32, v42, v65
	v_sub_f32_e32 v48, v48, v65
	v_exp_f32_e32 v76, v32
	v_sub_f32_e32 v32, v43, v65
	v_exp_f32_e32 v48, v48
	v_sub_f32_e32 v49, v49, v65
	v_exp_f32_e32 v77, v32
	v_sub_f32_e32 v32, v44, v65
	v_exp_f32_e32 v49, v49
	v_sub_f32_e32 v50, v50, v65
	v_sub_f32_e32 v55, v55, v65
	v_exp_f32_e32 v78, v32
	v_sub_f32_e32 v32, v45, v65
	v_exp_f32_e32 v50, v50
	v_sub_f32_e32 v51, v51, v65
	v_sub_f32_e32 v53, v53, v65
	v_exp_f32_e32 v55, v55
	v_exp_f32_e32 v79, v32
	v_sub_f32_e32 v32, v46, v65
	v_exp_f32_e32 v51, v51
	v_sub_f32_e32 v52, v52, v65
	v_exp_f32_e32 v53, v53
	v_sub_f32_e32 v54, v54, v65
	v_exp_f32_e32 v80, v32
	v_sub_f32_e32 v32, v47, v65
	v_sub_f32_e32 v64, v109, v65
	v_exp_f32_e32 v52, v52
	v_exp_f32_e32 v54, v54
	v_sub_f32_e32 v56, v56, v65
	v_sub_f32_e32 v57, v57, v65
	v_sub_f32_e32 v58, v58, v65
	v_sub_f32_e32 v59, v59, v65
	v_sub_f32_e32 v60, v60, v65
	v_sub_f32_e32 v61, v61, v65
	v_sub_f32_e32 v62, v62, v65
	v_sub_f32_e32 v63, v63, v65
	v_exp_f32_e32 v65, v32
	v_add_f32_e32 v32, 0, v48
	v_add_f32_e32 v32, v49, v32
	v_add_f32_e32 v44, v50, v32
	ds_read2_b64 v[32:35], v143 offset0:128 offset1:130
	v_exp_f32_e32 v64, v64
	v_cvt_pk_bf16_f32 v39, v54, v55
	v_cvt_pk_bf16_f32 v38, v52, v53
	v_cvt_pk_bf16_f32 v37, v50, v51
	v_cvt_pk_bf16_f32 v36, v48, v49
	ds_read2_b64 v[40:43], v142 offset0:128 offset1:130
	v_pk_mul_f32 v[30:31], v[30:31], v[64:65] op_sel_hi:[1,0]
	v_pk_mul_f32 v[28:29], v[28:29], v[64:65] op_sel_hi:[1,0]
	v_pk_mul_f32 v[26:27], v[26:27], v[64:65] op_sel_hi:[1,0]
	v_pk_mul_f32 v[24:25], v[24:25], v[64:65] op_sel_hi:[1,0]
	v_pk_mul_f32 v[22:23], v[22:23], v[64:65] op_sel_hi:[1,0]
	v_pk_mul_f32 v[20:21], v[20:21], v[64:65] op_sel_hi:[1,0]
	v_pk_mul_f32 v[18:19], v[18:19], v[64:65] op_sel_hi:[1,0]
	v_pk_mul_f32 v[16:17], v[16:17], v[64:65] op_sel_hi:[1,0]
	v_exp_f32_e32 v57, v57
	v_exp_f32_e32 v59, v59
	s_waitcnt lgkmcnt(1)
	v_mfma_f32_32x32x16_bf16 v[16:31], v[32:35], v[36:39], v[16:31]
	v_add_f32_e32 v32, v51, v44
	v_exp_f32_e32 v56, v56
	v_exp_f32_e32 v58, v58
	v_exp_f32_e32 v60, v60
	v_exp_f32_e32 v62, v62
	v_add_f32_e32 v32, v52, v32
	v_exp_f32_e32 v61, v61
	v_exp_f32_e32 v63, v63
	v_add_f32_e32 v32, v53, v32
	v_pk_mul_f32 v[14:15], v[14:15], v[64:65] op_sel_hi:[1,0]
	v_pk_mul_f32 v[12:13], v[12:13], v[64:65] op_sel_hi:[1,0]
	v_pk_mul_f32 v[10:11], v[10:11], v[64:65] op_sel_hi:[1,0]
	v_pk_mul_f32 v[8:9], v[8:9], v[64:65] op_sel_hi:[1,0]
	v_pk_mul_f32 v[6:7], v[6:7], v[64:65] op_sel_hi:[1,0]
	v_pk_mul_f32 v[4:5], v[4:5], v[64:65] op_sel_hi:[1,0]
	v_pk_mul_f32 v[2:3], v[2:3], v[64:65] op_sel_hi:[1,0]
	v_pk_mul_f32 v[0:1], v[0:1], v[64:65] op_sel_hi:[1,0]
	v_add_f32_e32 v32, v54, v32
	v_add_f32_e32 v48, v55, v32
	s_waitcnt lgkmcnt(0)
	v_mfma_f32_32x32x16_bf16 v[0:15], v[40:43], v[36:39], v[0:15]
	ds_read2_b64 v[32:35], v143 offset0:132 offset1:134
	ds_read2_b64 v[44:47], v142 offset0:132 offset1:134
	v_add_f32_e32 v40, v56, v48
	v_cvt_pk_bf16_f32 v39, v62, v63
	v_cvt_pk_bf16_f32 v38, v60, v61
	v_cvt_pk_bf16_f32 v37, v58, v59
	v_cvt_pk_bf16_f32 v36, v56, v57
	s_waitcnt lgkmcnt(1)
	s_nop 0
	v_mfma_f32_32x32x16_bf16 v[16:31], v[32:35], v[36:39], v[16:31]
	v_add_f32_e32 v32, v57, v40
	v_add_f32_e32 v32, v58, v32
	v_add_f32_e32 v32, v59, v32
	v_add_f32_e32 v32, v60, v32
	v_add_f32_e32 v32, v61, v32
	v_add_f32_e32 v32, v62, v32
	v_add_f32_e32 v32, v63, v32
	s_waitcnt lgkmcnt(0)
	v_mfma_f32_32x32x16_bf16 v[0:15], v[44:47], v[36:39], v[0:15]
	v_add_f32_e32 v44, v66, v32
	ds_read2_b64 v[32:35], v143 offset0:136 offset1:138
	v_cvt_pk_bf16_f32 v39, v72, v73
	v_cvt_pk_bf16_f32 v38, v70, v71
	v_cvt_pk_bf16_f32 v37, v68, v69
	v_cvt_pk_bf16_f32 v36, v66, v67
	ds_read2_b64 v[40:43], v142 offset0:136 offset1:138
	s_waitcnt lgkmcnt(1)
	v_mfma_f32_32x32x16_bf16 v[16:31], v[32:35], v[36:39], v[16:31]
	v_add_f32_e32 v32, v67, v44
	v_add_f32_e32 v32, v68, v32
	v_add_f32_e32 v32, v69, v32
	v_add_f32_e32 v32, v70, v32
	v_add_f32_e32 v32, v71, v32
	v_add_f32_e32 v32, v72, v32
	v_add_f32_e32 v32, v73, v32
	v_add_f32_e32 v32, v74, v32
	v_add_f32_e32 v32, v75, v32
	v_add_f32_e32 v32, v76, v32
	v_add_f32_e32 v32, v77, v32
	v_add_f32_e32 v32, v78, v32
	v_add_f32_e32 v32, v79, v32
	v_add_f32_e32 v32, v80, v32
	s_waitcnt lgkmcnt(0)
	v_mfma_f32_32x32x16_bf16 v[0:15], v[40:43], v[36:39], v[0:15]
	v_add_f32_e32 v40, v65, v32
	ds_read2_b64 v[32:35], v141 offset0:140 offset1:142
	v_fmac_f32_e32 v40, v108, v64
	v_cvt_pk_bf16_f32 v39, v80, v65
	ds_bpermute_b32 v41, v123, v40
	v_cvt_pk_bf16_f32 v38, v78, v79
	v_cvt_pk_bf16_f32 v37, v76, v77
	v_cvt_pk_bf16_f32 v36, v74, v75
	v_mov_b32_e32 v123, v117
	s_waitcnt lgkmcnt(0)
	v_add_f32_e32 v40, v40, v41
	v_mfma_f32_32x32x16_bf16 v[16:31], v[32:35], v[36:39], v[16:31]
	ds_read2_b64 v[32:35], v140 offset0:140 offset1:142
	v_div_scale_f32 v41, s[0:1], v40, v40, 1.0
	v_rcp_f32_e32 v42, v41
	s_waitcnt lgkmcnt(0)
	v_mfma_f32_32x32x16_bf16 v[0:15], v[32:35], v[36:39], v[0:15]
	v_fma_f32 v32, -v41, v42, 1.0
	v_fmac_f32_e32 v42, v32, v42
	v_div_scale_f32 v32, vcc, 1.0, v40, 1.0
	v_mul_f32_e32 v33, v32, v42
	v_fma_f32 v34, -v41, v33, v32
	v_fmac_f32_e32 v33, v34, v42
	v_fma_f32 v32, -v41, v33, v32
	v_div_fmas_f32 v32, v32, v42, v33
	v_div_fixup_f32 v32, v32, v40, 1.0
	v_mov_b32_e32 v38, v16
	v_mov_b32_e32 v39, v18
	v_mov_b32_e32 v18, v17
	v_lshlrev_b64 v[34:35], 11, v[118:119]
	v_pk_mul_f32 v[38:39], v[38:39], v[32:33] op_sel_hi:[1,0]
	v_pk_mul_f32 v[16:17], v[18:19], v[32:33] op_sel_hi:[1,0]
	v_lshl_add_u64 v[34:35], s[8:9], 0, v[34:35]
	v_and_b32_sdwa v19, v38, v155 dst_sel:DWORD dst_unused:UNUSED_PAD src0_sel:WORD_1 src1_sel:DWORD
	v_and_b32_sdwa v33, v17, v155 dst_sel:DWORD dst_unused:UNUSED_PAD src0_sel:WORD_1 src1_sel:DWORD
	v_lshl_add_u64 v[34:35], v[120:121], 1, v[34:35]
	v_and_b32_sdwa v18, v39, v155 dst_sel:DWORD dst_unused:UNUSED_PAD src0_sel:WORD_1 src1_sel:DWORD
	v_add3_u32 v19, v38, v19, s61
	v_and_b32_sdwa v38, v16, v155 dst_sel:DWORD dst_unused:UNUSED_PAD src0_sel:WORD_1 src1_sel:DWORD
	v_add3_u32 v17, v17, v33, s61
	v_lshl_add_u64 v[34:35], v[34:35], 0, v[122:123]
	v_add3_u32 v18, v39, v18, s61
	v_add3_u32 v16, v16, v38, s61
	v_and_b32_e32 v17, 0xffff0000, v17
	v_and_b32_e32 v16, 0xffff0000, v16
	v_or_b32_sdwa v17, v17, v18 dst_sel:DWORD dst_unused:UNUSED_PAD src0_sel:DWORD src1_sel:WORD_1
	v_add_co_u32_e32 v18, vcc, s63, v34
	v_or_b32_sdwa v16, v16, v19 dst_sel:DWORD dst_unused:UNUSED_PAD src0_sel:DWORD src1_sel:WORD_1
	s_nop 0
	v_addc_co_u32_e32 v19, vcc, 0, v35, vcc
	global_store_dwordx2 v[18:19], v[16:17], off offset:3840
	v_mov_b32_e32 v16, v20
	v_mov_b32_e32 v17, v22
	v_pk_mul_f32 v[16:17], v[16:17], v[32:33] op_sel_hi:[1,0]
	v_mov_b32_e32 v22, v21
	v_pk_mul_f32 v[18:19], v[22:23], v[32:33] op_sel_hi:[1,0]
	v_and_b32_sdwa v20, v17, v155 dst_sel:DWORD dst_unused:UNUSED_PAD src0_sel:WORD_1 src1_sel:DWORD
	v_and_b32_sdwa v21, v16, v155 dst_sel:DWORD dst_unused:UNUSED_PAD src0_sel:WORD_1 src1_sel:DWORD
	v_add3_u32 v16, v16, v21, s61
	v_add3_u32 v17, v17, v20, s61
	v_and_b32_sdwa v20, v19, v155 dst_sel:DWORD dst_unused:UNUSED_PAD src0_sel:WORD_1 src1_sel:DWORD
	v_and_b32_sdwa v21, v18, v155 dst_sel:DWORD dst_unused:UNUSED_PAD src0_sel:WORD_1 src1_sel:DWORD
	v_add3_u32 v19, v19, v20, s61
	v_add3_u32 v18, v18, v21, s61
	v_and_b32_e32 v19, 0xffff0000, v19
	v_and_b32_e32 v18, 0xffff0000, v18
	v_lshl_add_u64 v[36:37], v[34:35], 0, s[50:51]
	v_or_b32_sdwa v17, v19, v17 dst_sel:DWORD dst_unused:UNUSED_PAD src0_sel:DWORD src1_sel:WORD_1
	v_or_b32_sdwa v16, v18, v16 dst_sel:DWORD dst_unused:UNUSED_PAD src0_sel:DWORD src1_sel:WORD_1
	global_store_dwordx2 v[36:37], v[16:17], off offset:16
	v_mov_b32_e32 v16, v24
	v_mov_b32_e32 v17, v26
	v_pk_mul_f32 v[16:17], v[16:17], v[32:33] op_sel_hi:[1,0]
	v_mov_b32_e32 v26, v25
	v_pk_mul_f32 v[18:19], v[26:27], v[32:33] op_sel_hi:[1,0]
	v_and_b32_sdwa v20, v17, v155 dst_sel:DWORD dst_unused:UNUSED_PAD src0_sel:WORD_1 src1_sel:DWORD
	v_and_b32_sdwa v21, v16, v155 dst_sel:DWORD dst_unused:UNUSED_PAD src0_sel:WORD_1 src1_sel:DWORD
	v_add3_u32 v16, v16, v21, s61
	v_add3_u32 v17, v17, v20, s61
	v_and_b32_sdwa v20, v19, v155 dst_sel:DWORD dst_unused:UNUSED_PAD src0_sel:WORD_1 src1_sel:DWORD
	v_and_b32_sdwa v21, v18, v155 dst_sel:DWORD dst_unused:UNUSED_PAD src0_sel:WORD_1 src1_sel:DWORD
	v_add3_u32 v19, v19, v20, s61
	v_add3_u32 v18, v18, v21, s61
	v_and_b32_e32 v19, 0xffff0000, v19
	v_and_b32_e32 v18, 0xffff0000, v18
	v_or_b32_sdwa v17, v19, v17 dst_sel:DWORD dst_unused:UNUSED_PAD src0_sel:DWORD src1_sel:WORD_1
	v_or_b32_sdwa v16, v18, v16 dst_sel:DWORD dst_unused:UNUSED_PAD src0_sel:DWORD src1_sel:WORD_1
	global_store_dwordx2 v[36:37], v[16:17], off offset:32
	v_mov_b32_e32 v16, v28
	v_mov_b32_e32 v17, v30
	v_pk_mul_f32 v[16:17], v[16:17], v[32:33] op_sel_hi:[1,0]
	v_mov_b32_e32 v30, v29
	v_pk_mul_f32 v[18:19], v[30:31], v[32:33] op_sel_hi:[1,0]
	v_and_b32_sdwa v20, v17, v155 dst_sel:DWORD dst_unused:UNUSED_PAD src0_sel:WORD_1 src1_sel:DWORD
	v_and_b32_sdwa v21, v16, v155 dst_sel:DWORD dst_unused:UNUSED_PAD src0_sel:WORD_1 src1_sel:DWORD
	v_add3_u32 v16, v16, v21, s61
	v_add3_u32 v17, v17, v20, s61
	v_and_b32_sdwa v20, v19, v155 dst_sel:DWORD dst_unused:UNUSED_PAD src0_sel:WORD_1 src1_sel:DWORD
	v_and_b32_sdwa v21, v18, v155 dst_sel:DWORD dst_unused:UNUSED_PAD src0_sel:WORD_1 src1_sel:DWORD
	v_add3_u32 v19, v19, v20, s61
	v_add3_u32 v18, v18, v21, s61
	v_and_b32_e32 v19, 0xffff0000, v19
	v_and_b32_e32 v18, 0xffff0000, v18
	v_or_b32_sdwa v17, v19, v17 dst_sel:DWORD dst_unused:UNUSED_PAD src0_sel:DWORD src1_sel:WORD_1
	v_or_b32_sdwa v16, v18, v16 dst_sel:DWORD dst_unused:UNUSED_PAD src0_sel:DWORD src1_sel:WORD_1
	global_store_dwordx2 v[36:37], v[16:17], off offset:48
	v_mov_b32_e32 v16, v0
	v_mov_b32_e32 v17, v2
	v_pk_mul_f32 v[16:17], v[16:17], v[32:33] op_sel_hi:[1,0]
	v_mov_b32_e32 v2, v1
	v_pk_mul_f32 v[0:1], v[2:3], v[32:33] op_sel_hi:[1,0]
	v_and_b32_sdwa v2, v17, v155 dst_sel:DWORD dst_unused:UNUSED_PAD src0_sel:WORD_1 src1_sel:DWORD
	v_and_b32_sdwa v3, v16, v155 dst_sel:DWORD dst_unused:UNUSED_PAD src0_sel:WORD_1 src1_sel:DWORD
	v_add3_u32 v3, v16, v3, s61
	v_add3_u32 v2, v17, v2, s61
	v_and_b32_sdwa v16, v1, v155 dst_sel:DWORD dst_unused:UNUSED_PAD src0_sel:WORD_1 src1_sel:DWORD
	v_and_b32_sdwa v17, v0, v155 dst_sel:DWORD dst_unused:UNUSED_PAD src0_sel:WORD_1 src1_sel:DWORD
	v_add3_u32 v1, v1, v16, s61
	v_add3_u32 v0, v0, v17, s61
	v_and_b32_e32 v1, 0xffff0000, v1
	v_and_b32_e32 v0, 0xffff0000, v0
	v_or_b32_sdwa v1, v1, v2 dst_sel:DWORD dst_unused:UNUSED_PAD src0_sel:DWORD src1_sel:WORD_1
	v_or_b32_sdwa v0, v0, v3 dst_sel:DWORD dst_unused:UNUSED_PAD src0_sel:DWORD src1_sel:WORD_1
	global_store_dwordx2 v[36:37], v[0:1], off offset:64
	v_mov_b32_e32 v0, v4
	v_mov_b32_e32 v1, v6
	v_pk_mul_f32 v[0:1], v[0:1], v[32:33] op_sel_hi:[1,0]
	v_mov_b32_e32 v6, v5
	v_pk_mul_f32 v[2:3], v[6:7], v[32:33] op_sel_hi:[1,0]
	v_and_b32_sdwa v4, v1, v155 dst_sel:DWORD dst_unused:UNUSED_PAD src0_sel:WORD_1 src1_sel:DWORD
	v_and_b32_sdwa v5, v0, v155 dst_sel:DWORD dst_unused:UNUSED_PAD src0_sel:WORD_1 src1_sel:DWORD
	v_add3_u32 v0, v0, v5, s61
	v_add3_u32 v1, v1, v4, s61
	v_and_b32_sdwa v4, v3, v155 dst_sel:DWORD dst_unused:UNUSED_PAD src0_sel:WORD_1 src1_sel:DWORD
	v_and_b32_sdwa v5, v2, v155 dst_sel:DWORD dst_unused:UNUSED_PAD src0_sel:WORD_1 src1_sel:DWORD
	v_add3_u32 v3, v3, v4, s61
	v_add3_u32 v2, v2, v5, s61
	v_and_b32_e32 v3, 0xffff0000, v3
	v_and_b32_e32 v2, 0xffff0000, v2
	v_or_b32_sdwa v1, v3, v1 dst_sel:DWORD dst_unused:UNUSED_PAD src0_sel:DWORD src1_sel:WORD_1
	v_or_b32_sdwa v0, v2, v0 dst_sel:DWORD dst_unused:UNUSED_PAD src0_sel:DWORD src1_sel:WORD_1
	global_store_dwordx2 v[36:37], v[0:1], off offset:80
	v_mov_b32_e32 v0, v8
	v_mov_b32_e32 v1, v10
	v_pk_mul_f32 v[0:1], v[0:1], v[32:33] op_sel_hi:[1,0]
	v_mov_b32_e32 v10, v9
	v_pk_mul_f32 v[2:3], v[10:11], v[32:33] op_sel_hi:[1,0]
	v_and_b32_sdwa v4, v1, v155 dst_sel:DWORD dst_unused:UNUSED_PAD src0_sel:WORD_1 src1_sel:DWORD
	v_and_b32_sdwa v5, v0, v155 dst_sel:DWORD dst_unused:UNUSED_PAD src0_sel:WORD_1 src1_sel:DWORD
	v_add3_u32 v0, v0, v5, s61
	v_add3_u32 v1, v1, v4, s61
	v_and_b32_sdwa v4, v3, v155 dst_sel:DWORD dst_unused:UNUSED_PAD src0_sel:WORD_1 src1_sel:DWORD
	v_and_b32_sdwa v5, v2, v155 dst_sel:DWORD dst_unused:UNUSED_PAD src0_sel:WORD_1 src1_sel:DWORD
	v_add3_u32 v3, v3, v4, s61
	v_add3_u32 v2, v2, v5, s61
	v_and_b32_e32 v3, 0xffff0000, v3
	v_and_b32_e32 v2, 0xffff0000, v2
	v_or_b32_sdwa v1, v3, v1 dst_sel:DWORD dst_unused:UNUSED_PAD src0_sel:DWORD src1_sel:WORD_1
	v_or_b32_sdwa v0, v2, v0 dst_sel:DWORD dst_unused:UNUSED_PAD src0_sel:DWORD src1_sel:WORD_1
	global_store_dwordx2 v[36:37], v[0:1], off offset:96
	v_mov_b32_e32 v0, v12
	v_mov_b32_e32 v1, v14
	v_pk_mul_f32 v[0:1], v[0:1], v[32:33] op_sel_hi:[1,0]
	v_mov_b32_e32 v14, v13
	v_pk_mul_f32 v[2:3], v[14:15], v[32:33] op_sel_hi:[1,0]
	v_and_b32_sdwa v4, v1, v155 dst_sel:DWORD dst_unused:UNUSED_PAD src0_sel:WORD_1 src1_sel:DWORD
	v_and_b32_sdwa v5, v0, v155 dst_sel:DWORD dst_unused:UNUSED_PAD src0_sel:WORD_1 src1_sel:DWORD
	v_add3_u32 v0, v0, v5, s61
	v_add3_u32 v1, v1, v4, s61
	v_and_b32_sdwa v4, v3, v155 dst_sel:DWORD dst_unused:UNUSED_PAD src0_sel:WORD_1 src1_sel:DWORD
	v_and_b32_sdwa v5, v2, v155 dst_sel:DWORD dst_unused:UNUSED_PAD src0_sel:WORD_1 src1_sel:DWORD
	v_add3_u32 v3, v3, v4, s61
	v_add3_u32 v2, v2, v5, s61
	v_and_b32_e32 v3, 0xffff0000, v3
	v_and_b32_e32 v2, 0xffff0000, v2
	v_or_b32_sdwa v1, v3, v1 dst_sel:DWORD dst_unused:UNUSED_PAD src0_sel:DWORD src1_sel:WORD_1
	v_or_b32_sdwa v0, v2, v0 dst_sel:DWORD dst_unused:UNUSED_PAD src0_sel:DWORD src1_sel:WORD_1
	global_store_dwordx2 v[36:37], v[0:1], off offset:112
	s_branch .LBB0_1562
